# v18: v7 + gate|up K-loop with one barrier per load/MMA pair (per-half loop copies) and an s_sleep/s_wakeup MFMA hand-off hint
# speedup vs baseline: 1.0009x; 1.0009x over previous
.LBB0_1092:
	s_cmp_ge_i32 s33, s72
	s_cselect_b64 s[6:7], -1, 0
	s_cmp_lt_i32 s33, s73
	s_cselect_b64 s[0:1], -1, 0
	s_and_b64 s[0:1], s[6:7], s[0:1]
	s_andn2_b64 vcc, exec, s[0:1]
	s_cbranch_vccnz .LBB0_1157
	v_readlane_b32 s0, v254, 12
	s_waitcnt lgkmcnt(0)
	v_readlane_b32 s8, v254, 34
	v_mov_b32_e32 v0, s83
	ds_read_b32 v0, v0
	v_readlane_b32 s9, v254, 35
	s_ashr_i32 s9, s8, 31
	s_mov_b64 s[4:5], s[94:95]
	s_mov_b64 s[16:17], s[94:95]
	s_waitcnt lgkmcnt(0)
	v_readfirstlane_b32 s38, v0
	s_ashr_i32 s39, s38, 31
	s_lshr_b32 s0, s39, 29
	s_add_i32 s0, s38, s0
	s_ashr_i32 s33, s0, 3
	s_and_b32 s0, s0, -8
	s_sub_i32 s40, s38, s0
	s_cmp_lt_i32 s40, 0
	s_cselect_b64 s[0:1], -1, 0
	s_cmpk_gt_i32 s38, 0x15ff
	s_mov_b64 s[2:3], s[94:95]
	s_mov_b64 s[10:11], s[94:95]
	s_mov_b64 s[12:13], s[94:95]
	s_mov_b64 s[14:15], s[94:95]
	s_mov_b32 s24, s46
	v_mov_b32_e32 v172, v201
	s_waitcnt vmcnt(0)
	v_mbcnt_lo_u32_b32 v14, -1, 0
	v_mbcnt_hi_u32_b32 v14, -1, v14
	s_cbranch_scc1 .LBB0_1113
	s_load_dwordx2 s[4:5], s[4:5], 0xa8
	s_nop 0
	s_load_dwordx2 s[16:17], s[16:17], 0xa8
	s_mul_i32 s19, s8, 0x2c00000
	s_mul_hi_i32 s18, s8, 0x2c00000
	v_mov_b32_e32 v161, v201
	s_waitcnt lgkmcnt(0)
	s_add_u32 s48, s4, 0xe800000
	s_addc_u32 s49, s5, 0
	s_add_u32 s4, s16, s19
	s_addc_u32 s5, s17, s18
	s_add_u32 s50, s4, 0x5200000
	s_addc_u32 s51, s5, 0
	s_lshl_b32 s53, s24, 10
	v_lshl_or_b32 v0, v14, 4, s53
	v_add_u32_e32 v1, 0x2000, v0
	v_ashrrev_i32_e32 v2, 31, v1
	v_lshrrev_b32_e32 v2, 22, v2
	v_add_u32_e32 v2, v1, v2
	v_ashrrev_i32_e32 v8, 10, v2
	v_mul_i32_i24_e32 v2, 0x400, v8
	v_sub_u32_e32 v1, v1, v2
	v_lshrrev_b32_e32 v2, 4, v1
	v_bitop3_b32 v1, v2, v1, 32 bitop3:0x6c
	v_ashrrev_i32_e32 v2, 31, v1
	v_lshrrev_b32_e32 v2, 26, v2
	v_add_u32_e32 v2, v1, v2
	v_lshlrev_b32_e32 v3, 3, v8
	v_ashrrev_i32_e32 v9, 6, v2
	v_and_b32_e32 v3, -16, v3
	v_and_b32_e32 v2, 0xffc0, v2
	v_add_u32_e32 v3, v9, v3
	v_sub_u32_e32 v1, v1, v2
	v_and_b32_e32 v4, 3, v9
	s_mov_b32 s4, 0xfffe0
	v_lshrrev_b32_e32 v5, 2, v3
	v_lshlrev_b32_e32 v6, 1, v3
	v_lshrrev_b16_e32 v2, 7, v1
	v_and_or_b32 v4, v3, s4, v4
	v_and_b32_e32 v5, 4, v5
	v_and_b32_e32 v6, 24, v6
	v_and_b32_e32 v2, 1, v2
	v_or3_b32 v4, v4, v5, v6
	v_add_u16_e32 v1, v1, v2
	v_mov_b32_e32 v6, 1
	v_lshlrev_b32_e32 v5, 5, v8
	v_ashrrev_i16_sdwa v1, v6, sext(v1) dst_sel:DWORD dst_unused:UNUSED_PAD src0_sel:DWORD src1_sel:BYTE_0
	v_and_b32_e32 v5, 32, v5
	v_bfe_i32 v10, v1, 0, 16
	v_add_lshl_u32 v1, v5, v10, 1
	v_lshl_add_u32 v160, v4, 12, v1
	v_lshl_add_u32 v162, v3, 12, v1
	v_ashrrev_i32_e32 v1, 31, v0
	v_lshrrev_b32_e32 v1, 22, v1
	v_add_u32_e32 v1, v0, v1
	v_ashrrev_i32_e32 v11, 10, v1
	v_mul_i32_i24_e32 v1, 0x400, v11
	v_sub_u32_e32 v0, v0, v1
	v_lshrrev_b32_e32 v1, 4, v0
	v_bitop3_b32 v0, v1, v0, 32 bitop3:0x6c
	v_ashrrev_i32_e32 v1, 31, v0
	v_lshrrev_b32_e32 v1, 26, v1
	v_add_u32_e32 v1, v0, v1
	v_lshlrev_b32_e32 v2, 3, v11
	v_ashrrev_i32_e32 v12, 6, v1
	v_and_b32_e32 v2, -16, v2
	s_ashr_i32 s25, s24, 2
	v_add_u32_e32 v2, v12, v2
	v_and_b32_e32 v3, 3, v12
	v_and_or_b32 v3, v2, s4, v3
	s_and_b64 s[4:5], s[0:1], exec
	s_movk_i32 s4, 0x2c1
	s_cselect_b32 s4, s4, 0x2c0
	s_mul_i32 s4, s40, s4
	s_add_i32 s4, s4, s33
	s_mul_hi_i32 s5, s4, 0x2e8ba2e9
	s_lshr_b32 s16, s5, 31
	s_ashr_i32 s5, s5, 5
	s_add_i32 s5, s5, s16
	s_lshl_b32 s17, s5, 2
	s_mulk_i32 s5, 0xb0
	s_sub_i32 s4, s4, s5
	s_bfe_u32 s5, s4, 0x2001d
	s_add_i32 s5, s4, s5
	s_sext_i32_i16 s16, s5
	s_and_b32 s5, s5, 0xfffc
	s_sub_i32 s4, s4, s5
	s_sext_i32_i16 s4, s4
	v_lshrrev_b32_e32 v4, 2, v2
	v_lshlrev_b32_e32 v5, 1, v2
	v_and_b32_e32 v1, 0xc0, v1
	s_lshr_b32 s16, s16, 2
	s_add_i32 s30, s17, s4
	v_and_b32_e32 v4, 4, v4
	v_and_b32_e32 v5, 24, v5
	v_sub_u32_e32 v0, v0, v1
	s_ashr_i32 s31, s30, 31
	s_bfe_i64 s[18:19], s[16:17], 0x100000
	v_or3_b32 v3, v3, v4, v5
	v_lshlrev_b32_e32 v4, 5, v11
	v_ashrrev_i16_sdwa v0, v6, sext(v0) dst_sel:DWORD dst_unused:UNUSED_PAD src0_sel:DWORD src1_sel:BYTE_0
	s_lshl_b64 s[4:5], s[30:31], 20
	s_lshl_b64 s[18:19], s[18:19], 20
	v_and_b32_e32 v4, 32, v4
	v_bfe_i32 v13, v0, 0, 16
	s_add_u32 s34, s50, s18
	v_add_lshl_u32 v0, v4, v13, 1
	s_addc_u32 s35, s51, s19
	s_add_i32 s31, s53, 0
	v_lshl_add_u32 v200, v3, 12, v0
	s_add_i32 m0, s31, 0x10000
	v_lshl_add_u32 v164, v2, 12, v0
	global_load_lds_dwordx4 v200, s[34:35]
	s_add_i32 m0, s31, 0x12000
	s_add_u32 s18, s34, 0x80000
	global_load_lds_dwordx4 v160, s[34:35]
	s_addc_u32 s19, s35, 0
	s_add_i32 m0, s31, 0x14000
	v_mov_b32_e32 v165, v201
	global_load_lds_dwordx4 v200, s[18:19]
	s_add_i32 m0, s31, 0x16000
	s_add_u32 s4, s48, s4
	s_addc_u32 s5, s49, s5
	s_add_i32 s42, s31, 0x2000
	global_load_lds_dwordx4 v160, s[18:19]
	s_mov_b32 m0, s31
	s_add_u32 s18, s4, 0x80000
	global_load_lds_dwordx4 v164, s[4:5]
	s_mov_b32 m0, s42
	s_addc_u32 s19, s5, 0
	s_add_i32 s43, s31, 0x4000
	global_load_lds_dwordx4 v162, s[4:5]
	s_mov_b32 m0, s43
	s_add_i32 s54, s31, 0x6000
	global_load_lds_dwordx4 v164, s[18:19]
	s_mov_b32 m0, s54
	v_mov_b32_e32 v163, v201
	global_load_lds_dwordx4 v162, s[18:19]
	s_load_dwordx2 s[22:23], s[2:3], 0xa8
	s_load_dwordx2 s[20:21], s[10:11], 0xa8
	s_load_dwordx2 s[18:19], s[12:13], 0xa8
	s_nop 0
	s_load_dwordx2 s[2:3], s[14:15], 0xa8
	s_cmp_eq_u32 s25, 1
	v_lshl_add_u64 v[6:7], s[34:35], 0, v[200:201]
	v_lshl_add_u64 v[4:5], s[34:35], 0, v[160:161]
	v_lshl_add_u64 v[0:1], s[4:5], 0, v[164:165]
	s_cselect_b64 s[10:11], -1, 0
	s_cmp_lg_u32 s25, 1
	v_lshl_add_u64 v[2:3], s[4:5], 0, v[162:163]
.LBB0_1096:
	s_waitcnt lgkmcnt(0)
	s_add_u32 s12, s22, 0x400000
	s_addc_u32 s13, s23, 0
	s_mul_i32 s17, s8, 0x16000
	s_sext_i32_i16 s60, s16
	s_mul_hi_i32 s16, s8, 0x16000
	s_add_u32 s14, s20, s17
	s_addc_u32 s15, s21, s16
	s_add_u32 s14, s14, 0x1000000
	s_addc_u32 s15, s15, 0
	s_add_u32 s17, s18, s17
	s_addc_u32 s18, s19, s16
	s_add_u32 s16, s17, 0x100b000
	s_addc_u32 s17, s18, 0
	v_and_b32_e32 v15, 15, v14
	s_add_u32 s18, s2, 0x16800000
	v_and_b32_e32 v16, 48, v14
	v_lshlrev_b32_e32 v15, 6, v15
	v_lshlrev_b32_e32 v14, 2, v14
	s_addc_u32 s19, s3, 0
	v_or_b32_e32 v17, v15, v16
	s_lshl_b32 s2, s25, 13
	v_and_b32_e32 v14, 32, v14
	v_bitop3_b32 v15, v15, v14, v16 bitop3:0x36
	v_bitop3_b32 v14, v17, s2, v14 bitop3:0xde
	s_lshl_b32 s2, s24, 12
	s_add_i32 m0, s31, 0x18000
	v_lshl_add_u64 v[6:7], v[6:7], 0, s[64:65]
	s_and_b32 s2, s2, 0x3000
	s_waitcnt vmcnt(2)
	s_barrier
	global_load_lds_dwordx4 v[6:7], off
	v_lshl_add_u64 v[4:5], v[4:5], 0, s[64:65]
	s_add_i32 m0, s31, 0x1a000
	s_add_i32 s55, s31, 0x8000
	s_add_i32 s56, s31, 0xa000
	v_or_b32_e32 v173, s2, v15
	global_load_lds_dwordx4 v[4:5], off
	v_lshl_add_u64 v[0:1], v[0:1], 0, s[64:65]
	s_mov_b32 m0, s55
	s_add_u32 s2, s34, 0x80080
	global_load_lds_dwordx4 v[0:1], off
	v_lshl_add_u64 v[0:1], v[2:3], 0, s[64:65]
	s_mov_b32 m0, s56
	s_addc_u32 s3, s35, 0
	global_load_lds_dwordx4 v[0:1], off
	s_add_i32 m0, s31, 0x1c000
	v_lshl_add_u64 v[0:1], s[2:3], 0, v[200:201]
	global_load_lds_dwordx4 v[0:1], off
	v_lshl_add_u64 v[0:1], s[2:3], 0, v[160:161]
	s_add_i32 m0, s31, 0x1e000
	s_cmp_lt_u32 s24, 4
	global_load_lds_dwordx4 v[0:1], off
	v_lshlrev_b32_e32 v0, 15, v11
	v_and_b32_e32 v0, 0xffff0000, v0
	v_lshl_add_u32 v0, v12, 12, v0
	v_and_b32_e32 v1, 1, v11
	v_lshl_or_b32 v0, v1, 6, v0
	v_lshl_add_u32 v166, v13, 1, v0
	v_lshlrev_b32_e32 v0, 15, v8
	v_and_b32_e32 v0, 0xffff0000, v0
	s_waitcnt vmcnt(6)
	v_lshl_add_u32 v0, v9, 12, v0
	v_and_b32_e32 v1, 1, v8
	v_lshl_or_b32 v0, v1, 6, v0
	s_cselect_b64 s[20:21], -1, 0
	v_mov_b32_e32 v167, v201
	v_lshl_add_u32 v168, v10, 1, v0
	v_mov_b32_e32 v169, v201
	s_mov_b32 s58, 0
	s_mov_b32 s59, -1
	v_add_u32_e32 v174, 0, v14
	s_barrier
	s_branch .LBB0_1099

.LBB0_1101:
	s_ashr_i32 s25, s24, 31
	s_lshl_b64 s[26:27], s[24:25], 20
	s_add_u32 s26, s48, s26
	s_addc_u32 s27, s49, s27
	s_and_b64 s[28:29], s[2:3], exec
	s_cselect_b32 s25, s27, s5
	s_cselect_b32 s61, s26, s4
	s_ashr_i32 s23, s22, 31
	s_lshl_b64 s[28:29], s[22:23], 20
	s_add_u32 s28, s50, s28
	s_addc_u32 s29, s51, s29
	s_and_b64 s[36:37], s[2:3], exec
	s_cselect_b32 s23, s29, s35
	s_cselect_b32 s62, s28, s34
	s_add_u32 s4, s4, 0x80080
	s_addc_u32 s5, s5, 0
	s_add_u32 s63, s34, 0x100
	s_addc_u32 s66, s35, 0
	s_mov_b32 s67, -2
	v_mov_b32_e32 v0, v172
	v_mov_b32_e32 v1, v172
	v_mov_b32_e32 v2, v172
	v_mov_b32_e32 v3, v172
	v_mov_b32_e32 v8, v172
	v_mov_b32_e32 v9, v172
	v_mov_b32_e32 v10, v172
	v_mov_b32_e32 v11, v172
	v_mov_b32_e32 v16, v172
	v_mov_b32_e32 v17, v172
	v_mov_b32_e32 v18, v172
	v_mov_b32_e32 v19, v172
	v_mov_b32_e32 v24, v172
	v_mov_b32_e32 v25, v172
	v_mov_b32_e32 v26, v172
	v_mov_b32_e32 v27, v172
	v_mov_b32_e32 v32, v172
	v_mov_b32_e32 v33, v172
	v_mov_b32_e32 v34, v172
	v_mov_b32_e32 v35, v172
	v_mov_b32_e32 v40, v172
	v_mov_b32_e32 v41, v172
	v_mov_b32_e32 v42, v172
	v_mov_b32_e32 v43, v172
	v_mov_b32_e32 v48, v172
	v_mov_b32_e32 v49, v172
	v_mov_b32_e32 v50, v172
	v_mov_b32_e32 v51, v172
	v_mov_b32_e32 v56, v172
	v_mov_b32_e32 v57, v172
	v_mov_b32_e32 v58, v172
	v_mov_b32_e32 v59, v172
	v_mov_b32_e32 v4, v172
	v_mov_b32_e32 v5, v172
	v_mov_b32_e32 v6, v172
	v_mov_b32_e32 v7, v172
	v_mov_b32_e32 v12, v172
	v_mov_b32_e32 v13, v172
	v_mov_b32_e32 v14, v172
	v_mov_b32_e32 v15, v172
	v_mov_b32_e32 v20, v172
	v_mov_b32_e32 v21, v172
	v_mov_b32_e32 v22, v172
	v_mov_b32_e32 v23, v172
	v_mov_b32_e32 v28, v172
	v_mov_b32_e32 v29, v172
	v_mov_b32_e32 v30, v172
	v_mov_b32_e32 v31, v172
	v_mov_b32_e32 v36, v172
	v_mov_b32_e32 v37, v172
	v_mov_b32_e32 v38, v172
	v_mov_b32_e32 v39, v172
	v_mov_b32_e32 v44, v172
	v_mov_b32_e32 v45, v172
	v_mov_b32_e32 v46, v172
	v_mov_b32_e32 v47, v172
	v_mov_b32_e32 v52, v172
	v_mov_b32_e32 v53, v172
	v_mov_b32_e32 v54, v172
	v_mov_b32_e32 v55, v172
	v_mov_b32_e32 v60, v172
	v_mov_b32_e32 v61, v172
	v_mov_b32_e32 v62, v172
	v_mov_b32_e32 v63, v172
	v_mov_b32_e32 v64, v172
	v_mov_b32_e32 v65, v172
	v_mov_b32_e32 v66, v172
	v_mov_b32_e32 v67, v172
	v_mov_b32_e32 v88, v172
	v_mov_b32_e32 v89, v172
	v_mov_b32_e32 v90, v172
	v_mov_b32_e32 v91, v172
	v_mov_b32_e32 v112, v172
	v_mov_b32_e32 v113, v172
	v_mov_b32_e32 v114, v172
	v_mov_b32_e32 v115, v172
	v_mov_b32_e32 v120, v172
	v_mov_b32_e32 v121, v172
	v_mov_b32_e32 v122, v172
	v_mov_b32_e32 v123, v172
	v_mov_b32_e32 v128, v172
	v_mov_b32_e32 v129, v172
	v_mov_b32_e32 v130, v172
	v_mov_b32_e32 v131, v172
	v_mov_b32_e32 v136, v172
	v_mov_b32_e32 v137, v172
	v_mov_b32_e32 v138, v172
	v_mov_b32_e32 v139, v172
	v_mov_b32_e32 v144, v172
	v_mov_b32_e32 v145, v172
	v_mov_b32_e32 v146, v172
	v_mov_b32_e32 v147, v172
	v_mov_b32_e32 v148, v172
	v_mov_b32_e32 v149, v172
	v_mov_b32_e32 v150, v172
	v_mov_b32_e32 v151, v172
	v_mov_b32_e32 v68, v172
	v_mov_b32_e32 v69, v172
	v_mov_b32_e32 v70, v172
	v_mov_b32_e32 v71, v172
	v_mov_b32_e32 v92, v172
	v_mov_b32_e32 v93, v172
	v_mov_b32_e32 v94, v172
	v_mov_b32_e32 v95, v172
	v_mov_b32_e32 v116, v172
	v_mov_b32_e32 v117, v172
	v_mov_b32_e32 v118, v172
	v_mov_b32_e32 v119, v172
	v_mov_b32_e32 v124, v172
	v_mov_b32_e32 v125, v172
	v_mov_b32_e32 v126, v172
	v_mov_b32_e32 v127, v172
	v_mov_b32_e32 v132, v172
	v_mov_b32_e32 v133, v172
	v_mov_b32_e32 v134, v172
	v_mov_b32_e32 v135, v172
	v_mov_b32_e32 v140, v172
	v_mov_b32_e32 v141, v172
	v_mov_b32_e32 v142, v172
	v_mov_b32_e32 v143, v172
	v_mov_b32_e32 v152, v172
	v_mov_b32_e32 v153, v172
	v_mov_b32_e32 v154, v172
	v_mov_b32_e32 v155, v172
	v_mov_b32_e32 v156, v172
	v_mov_b32_e32 v157, v172
	v_mov_b32_e32 v158, v172
	v_mov_b32_e32 v159, v172
	s_cmp_lt_u32 s46, 4
	s_cbranch_scc0 .Lhd1102_B
.LBB0_1102:
	s_add_u32 s34, s4, 0xfff80080
	s_addc_u32 s35, s5, -1
	s_add_i32 s68, 0, 0x10000
	s_cmp_eq_u32 s67, 28
	s_cselect_b32 s37, s25, s35
	s_cselect_b32 s36, s61, s34
	s_cselect_b32 s35, s23, s66
	s_cselect_b32 s34, s62, s63
	s_add_i32 s70, 0, 0x14000
	v_add_u32_e32 v84, s68, v173
	v_add_u32_e32 v108, s70, v173
	ds_read_b128 v[72:75], v84
	ds_read_b128 v[76:79], v84 offset:1024
	ds_read_b128 v[80:83], v84 offset:2048
	ds_read_b128 v[84:87], v84 offset:3072
	ds_read_b128 v[96:99], v108
	ds_read_b128 v[100:103], v108 offset:1024
	ds_read_b128 v[104:107], v108 offset:2048
	ds_read_b128 v[108:111], v108 offset:3072
	v_lshl_add_u64 v[170:171], s[4:5], 0, v[166:167]
	s_add_i32 m0, s31, 0xc000
	ds_read_b128 v[176:179], v174
	ds_read_b128 v[180:183], v174 offset:1024
	ds_read_b128 v[184:187], v174 offset:2048
	ds_read_b128 v[188:191], v174 offset:3072
	ds_read_b128 v[192:195], v174 offset:4096
	ds_read_b128 v[196:199], v174 offset:5120
	ds_read_b128 v[202:205], v174 offset:6144
	ds_read_b128 v[206:209], v174 offset:7168
	global_load_lds_dwordx4 v[170:171], off
	v_lshl_add_u64 v[170:171], s[4:5], 0, v[168:169]
	s_add_i32 m0, s31, 0xe000
	s_nop 0
	global_load_lds_dwordx4 v[170:171], off
	s_add_u32 vcc_lo, s4, 0xfff80000
	s_addc_u32 vcc_hi, s5, -1
	s_mov_b32 m0, s55
	s_nop 0
	global_load_lds_dwordx4 v164, vcc
	s_mov_b32 m0, s56
	s_nop 0
	global_load_lds_dwordx4 v162, vcc
	s_waitcnt vmcnt(4)
	s_waitcnt lgkmcnt(0)
	s_barrier
	s_setprio 2
	v_mfma_f32_16x16x32_bf16 v[156:159], v[72:75], v[176:179], v[156:159]
	v_mfma_f32_16x16x32_bf16 v[152:155], v[80:83], v[176:179], v[152:155]
	v_mfma_f32_16x16x32_bf16 v[140:143], v[72:75], v[184:187], v[140:143]
	v_mfma_f32_16x16x32_bf16 v[132:135], v[80:83], v[184:187], v[132:135]
	v_mfma_f32_16x16x32_bf16 v[124:127], v[72:75], v[192:195], v[124:127]
	v_mfma_f32_16x16x32_bf16 v[116:119], v[80:83], v[192:195], v[116:119]
	v_mfma_f32_16x16x32_bf16 v[92:95], v[72:75], v[202:205], v[92:95]
	v_mfma_f32_16x16x32_bf16 v[68:71], v[80:83], v[202:205], v[68:71]
	v_mfma_f32_16x16x32_bf16 v[156:159], v[76:79], v[180:183], v[156:159]
	v_mfma_f32_16x16x32_bf16 v[152:155], v[84:87], v[180:183], v[152:155]
	v_mfma_f32_16x16x32_bf16 v[140:143], v[76:79], v[188:191], v[140:143]
	v_mfma_f32_16x16x32_bf16 v[132:135], v[84:87], v[188:191], v[132:135]
	v_mfma_f32_16x16x32_bf16 v[124:127], v[76:79], v[196:199], v[124:127]
	v_mfma_f32_16x16x32_bf16 v[116:119], v[84:87], v[196:199], v[116:119]
	v_mfma_f32_16x16x32_bf16 v[92:95], v[76:79], v[206:209], v[92:95]
	v_mfma_f32_16x16x32_bf16 v[68:71], v[84:87], v[206:209], v[68:71]
	v_mfma_f32_16x16x32_bf16 v[148:151], v[96:99], v[176:179], v[148:151]
	v_mfma_f32_16x16x32_bf16 v[144:147], v[104:107], v[176:179], v[144:147]
	v_mfma_f32_16x16x32_bf16 v[136:139], v[96:99], v[184:187], v[136:139]
	v_mfma_f32_16x16x32_bf16 v[128:131], v[104:107], v[184:187], v[128:131]
	v_mfma_f32_16x16x32_bf16 v[120:123], v[96:99], v[192:195], v[120:123]
	v_mfma_f32_16x16x32_bf16 v[112:115], v[104:107], v[192:195], v[112:115]
	v_mfma_f32_16x16x32_bf16 v[88:91], v[96:99], v[202:205], v[88:91]
	v_mfma_f32_16x16x32_bf16 v[64:67], v[104:107], v[202:205], v[64:67]
	v_mfma_f32_16x16x32_bf16 v[148:151], v[100:103], v[180:183], v[148:151]
	v_mfma_f32_16x16x32_bf16 v[144:147], v[108:111], v[180:183], v[144:147]
	v_mfma_f32_16x16x32_bf16 v[136:139], v[100:103], v[188:191], v[136:139]
	v_mfma_f32_16x16x32_bf16 v[128:131], v[108:111], v[188:191], v[128:131]
	v_mfma_f32_16x16x32_bf16 v[120:123], v[100:103], v[196:199], v[120:123]
	v_mfma_f32_16x16x32_bf16 v[112:115], v[108:111], v[196:199], v[112:115]
	v_mfma_f32_16x16x32_bf16 v[88:91], v[100:103], v[206:209], v[88:91]
	v_mfma_f32_16x16x32_bf16 v[64:67], v[108:111], v[206:209], v[64:67]
	s_wakeup
	s_setprio 0
	s_add_i32 s68, s68, s53
	v_lshl_add_u64 v[170:171], s[34:35], 0, v[200:201]
	s_mov_b32 m0, s68
	ds_read_b128 v[176:179], v174 offset:16384
	ds_read_b128 v[180:183], v174 offset:17408
	ds_read_b128 v[184:187], v174 offset:18432
	ds_read_b128 v[188:191], v174 offset:19456
	ds_read_b128 v[192:195], v174 offset:20480
	ds_read_b128 v[196:199], v174 offset:21504
	ds_read_b128 v[202:205], v174 offset:22528
	ds_read_b128 v[206:209], v174 offset:23552
	global_load_lds_dwordx4 v[170:171], off
	s_add_i32 m0, s68, 0x2000
	s_add_u32 s68, s34, 0x80000
	v_lshl_add_u64 v[212:213], s[34:35], 0, v[160:161]
	s_addc_u32 s69, s35, 0
	s_add_i32 s70, s70, s53
	global_load_lds_dwordx4 v[212:213], off
	v_lshl_add_u64 v[214:215], s[68:69], 0, v[200:201]
	s_mov_b32 m0, s70
	global_load_lds_dwordx4 v[214:215], off
	v_lshl_add_u64 v[214:215], s[68:69], 0, v[160:161]
	s_add_i32 m0, s70, 0x2000
	s_nop 0
	global_load_lds_dwordx4 v[214:215], off
	s_waitcnt vmcnt(4)
	s_waitcnt lgkmcnt(0)
	s_barrier
	s_setprio 2
	v_mfma_f32_16x16x32_bf16 v[60:63], v[72:75], v[176:179], v[60:63]
	v_mfma_f32_16x16x32_bf16 v[52:55], v[80:83], v[176:179], v[52:55]
	v_mfma_f32_16x16x32_bf16 v[44:47], v[72:75], v[184:187], v[44:47]
	v_mfma_f32_16x16x32_bf16 v[36:39], v[80:83], v[184:187], v[36:39]
	v_mfma_f32_16x16x32_bf16 v[28:31], v[72:75], v[192:195], v[28:31]
	v_mfma_f32_16x16x32_bf16 v[20:23], v[80:83], v[192:195], v[20:23]
	v_mfma_f32_16x16x32_bf16 v[12:15], v[72:75], v[202:205], v[12:15]
	v_mfma_f32_16x16x32_bf16 v[4:7], v[80:83], v[202:205], v[4:7]
	v_mfma_f32_16x16x32_bf16 v[60:63], v[76:79], v[180:183], v[60:63]
	v_mfma_f32_16x16x32_bf16 v[52:55], v[84:87], v[180:183], v[52:55]
	v_mfma_f32_16x16x32_bf16 v[44:47], v[76:79], v[188:191], v[44:47]
	v_mfma_f32_16x16x32_bf16 v[36:39], v[84:87], v[188:191], v[36:39]
	v_mfma_f32_16x16x32_bf16 v[28:31], v[76:79], v[196:199], v[28:31]
	v_mfma_f32_16x16x32_bf16 v[20:23], v[84:87], v[196:199], v[20:23]
	v_mfma_f32_16x16x32_bf16 v[12:15], v[76:79], v[206:209], v[12:15]
	v_mfma_f32_16x16x32_bf16 v[4:7], v[84:87], v[206:209], v[4:7]
	v_mfma_f32_16x16x32_bf16 v[56:59], v[96:99], v[176:179], v[56:59]
	v_mfma_f32_16x16x32_bf16 v[48:51], v[104:107], v[176:179], v[48:51]
	v_mfma_f32_16x16x32_bf16 v[40:43], v[96:99], v[184:187], v[40:43]
	v_mfma_f32_16x16x32_bf16 v[32:35], v[104:107], v[184:187], v[32:35]
	v_mfma_f32_16x16x32_bf16 v[24:27], v[96:99], v[192:195], v[24:27]
	v_mfma_f32_16x16x32_bf16 v[16:19], v[104:107], v[192:195], v[16:19]
	v_mfma_f32_16x16x32_bf16 v[8:11], v[96:99], v[202:205], v[8:11]
	v_mfma_f32_16x16x32_bf16 v[0:3], v[104:107], v[202:205], v[0:3]
	v_mfma_f32_16x16x32_bf16 v[56:59], v[100:103], v[180:183], v[56:59]
	v_mfma_f32_16x16x32_bf16 v[48:51], v[108:111], v[180:183], v[48:51]
	v_mfma_f32_16x16x32_bf16 v[40:43], v[100:103], v[188:191], v[40:43]
	v_mfma_f32_16x16x32_bf16 v[32:35], v[108:111], v[188:191], v[32:35]
	v_mfma_f32_16x16x32_bf16 v[24:27], v[100:103], v[196:199], v[24:27]
	v_mfma_f32_16x16x32_bf16 v[16:19], v[108:111], v[196:199], v[16:19]
	v_mfma_f32_16x16x32_bf16 v[8:11], v[100:103], v[206:209], v[8:11]
	v_mfma_f32_16x16x32_bf16 v[0:3], v[108:111], v[206:209], v[0:3]
	s_wakeup
	s_setprio 0
	s_add_i32 s68, 0, 0x18000
	s_add_i32 s69, 0, 0x1c000
	v_add_u32_e32 v84, s68, v173
	v_add_u32_e32 v108, s69, v173
	ds_read_b128 v[72:75], v84
	ds_read_b128 v[76:79], v84 offset:1024
	ds_read_b128 v[80:83], v84 offset:2048
	ds_read_b128 v[84:87], v84 offset:3072
	ds_read_b128 v[96:99], v108
	ds_read_b128 v[100:103], v108 offset:1024
	ds_read_b128 v[104:107], v108 offset:2048
	ds_read_b128 v[108:111], v108 offset:3072
	s_mov_b32 m0, s31
	s_nop 0
	global_load_lds_dwordx4 v164, s[36:37]
	s_mov_b32 m0, s42
	s_nop 0
	global_load_lds_dwordx4 v162, s[36:37]
	s_add_u32 s36, s36, 0x80000
	s_addc_u32 s37, s37, 0
	s_mov_b32 m0, s43
	v_lshl_add_u64 v[218:219], s[36:37], 0, v[164:165]
	ds_read_b128 v[176:179], v174 offset:32768
	ds_read_b128 v[180:183], v174 offset:33792
	ds_read_b128 v[184:187], v174 offset:34816
	ds_read_b128 v[188:191], v174 offset:35840
	ds_read_b128 v[192:195], v174 offset:36864
	ds_read_b128 v[196:199], v174 offset:37888
	ds_read_b128 v[202:205], v174 offset:38912
	ds_read_b128 v[206:209], v174 offset:39936
	global_load_lds_dwordx4 v[218:219], off
	v_lshl_add_u64 v[218:219], s[36:37], 0, v[162:163]
	s_mov_b32 m0, s54
	s_nop 0
	global_load_lds_dwordx4 v[218:219], off
	s_waitcnt vmcnt(4)
	s_waitcnt lgkmcnt(0)
	s_barrier
	s_setprio 2
	v_mfma_f32_16x16x32_bf16 v[156:159], v[72:75], v[176:179], v[156:159]
	v_mfma_f32_16x16x32_bf16 v[152:155], v[80:83], v[176:179], v[152:155]
	v_mfma_f32_16x16x32_bf16 v[140:143], v[72:75], v[184:187], v[140:143]
	v_mfma_f32_16x16x32_bf16 v[132:135], v[80:83], v[184:187], v[132:135]
	v_mfma_f32_16x16x32_bf16 v[124:127], v[72:75], v[192:195], v[124:127]
	v_mfma_f32_16x16x32_bf16 v[116:119], v[80:83], v[192:195], v[116:119]
	v_mfma_f32_16x16x32_bf16 v[92:95], v[72:75], v[202:205], v[92:95]
	v_mfma_f32_16x16x32_bf16 v[68:71], v[80:83], v[202:205], v[68:71]
	v_mfma_f32_16x16x32_bf16 v[156:159], v[76:79], v[180:183], v[156:159]
	v_mfma_f32_16x16x32_bf16 v[152:155], v[84:87], v[180:183], v[152:155]
	v_mfma_f32_16x16x32_bf16 v[140:143], v[76:79], v[188:191], v[140:143]
	v_mfma_f32_16x16x32_bf16 v[132:135], v[84:87], v[188:191], v[132:135]
	v_mfma_f32_16x16x32_bf16 v[124:127], v[76:79], v[196:199], v[124:127]
	v_mfma_f32_16x16x32_bf16 v[116:119], v[84:87], v[196:199], v[116:119]
	v_mfma_f32_16x16x32_bf16 v[92:95], v[76:79], v[206:209], v[92:95]
	v_mfma_f32_16x16x32_bf16 v[68:71], v[84:87], v[206:209], v[68:71]
	v_mfma_f32_16x16x32_bf16 v[148:151], v[96:99], v[176:179], v[148:151]
	v_mfma_f32_16x16x32_bf16 v[144:147], v[104:107], v[176:179], v[144:147]
	v_mfma_f32_16x16x32_bf16 v[136:139], v[96:99], v[184:187], v[136:139]
	v_mfma_f32_16x16x32_bf16 v[128:131], v[104:107], v[184:187], v[128:131]
	v_mfma_f32_16x16x32_bf16 v[120:123], v[96:99], v[192:195], v[120:123]
	v_mfma_f32_16x16x32_bf16 v[112:115], v[104:107], v[192:195], v[112:115]
	v_mfma_f32_16x16x32_bf16 v[88:91], v[96:99], v[202:205], v[88:91]
	v_mfma_f32_16x16x32_bf16 v[64:67], v[104:107], v[202:205], v[64:67]
	v_mfma_f32_16x16x32_bf16 v[148:151], v[100:103], v[180:183], v[148:151]
	v_mfma_f32_16x16x32_bf16 v[144:147], v[108:111], v[180:183], v[144:147]
	v_mfma_f32_16x16x32_bf16 v[136:139], v[100:103], v[188:191], v[136:139]
	v_mfma_f32_16x16x32_bf16 v[128:131], v[108:111], v[188:191], v[128:131]
	v_mfma_f32_16x16x32_bf16 v[120:123], v[100:103], v[196:199], v[120:123]
	v_mfma_f32_16x16x32_bf16 v[112:115], v[108:111], v[196:199], v[112:115]
	v_mfma_f32_16x16x32_bf16 v[88:91], v[100:103], v[206:209], v[88:91]
	v_mfma_f32_16x16x32_bf16 v[64:67], v[108:111], v[206:209], v[64:67]
	s_wakeup
	s_setprio 0
	s_add_i32 s36, s68, s53
	v_lshl_add_u64 v[170:171], v[170:171], 0, s[64:65]
	s_mov_b32 m0, s36
	ds_read_b128 v[176:179], v174 offset:49152
	ds_read_b128 v[180:183], v174 offset:50176
	ds_read_b128 v[184:187], v174 offset:51200
	ds_read_b128 v[188:191], v174 offset:52224
	ds_read_b128 v[192:195], v174 offset:53248
	ds_read_b128 v[196:199], v174 offset:54272
	ds_read_b128 v[202:205], v174 offset:55296
	ds_read_b128 v[206:209], v174 offset:56320
	global_load_lds_dwordx4 v[170:171], off
	s_add_i32 m0, s36, 0x2000
	s_add_u32 s34, s34, 0x80080
	v_lshl_add_u64 v[170:171], v[212:213], 0, s[64:65]
	s_addc_u32 s35, s35, 0
	s_add_i32 s36, s69, s53
	global_load_lds_dwordx4 v[170:171], off
	v_lshl_add_u64 v[170:171], s[34:35], 0, v[200:201]
	s_mov_b32 m0, s36
	s_nop 0
	global_load_lds_dwordx4 v[170:171], off
	v_lshl_add_u64 v[170:171], s[34:35], 0, v[160:161]
	s_add_i32 m0, s36, 0x2000
	s_nop 0
	global_load_lds_dwordx4 v[170:171], off
	s_waitcnt vmcnt(4)
	s_waitcnt lgkmcnt(0)
	s_barrier
	s_setprio 2
	v_mfma_f32_16x16x32_bf16 v[60:63], v[72:75], v[176:179], v[60:63]
	v_mfma_f32_16x16x32_bf16 v[52:55], v[80:83], v[176:179], v[52:55]
	v_mfma_f32_16x16x32_bf16 v[44:47], v[72:75], v[184:187], v[44:47]
	v_mfma_f32_16x16x32_bf16 v[36:39], v[80:83], v[184:187], v[36:39]
	v_mfma_f32_16x16x32_bf16 v[28:31], v[72:75], v[192:195], v[28:31]
	v_mfma_f32_16x16x32_bf16 v[20:23], v[80:83], v[192:195], v[20:23]
	v_mfma_f32_16x16x32_bf16 v[12:15], v[72:75], v[202:205], v[12:15]
	v_mfma_f32_16x16x32_bf16 v[4:7], v[80:83], v[202:205], v[4:7]
	v_mfma_f32_16x16x32_bf16 v[60:63], v[76:79], v[180:183], v[60:63]
	v_mfma_f32_16x16x32_bf16 v[52:55], v[84:87], v[180:183], v[52:55]
	v_mfma_f32_16x16x32_bf16 v[44:47], v[76:79], v[188:191], v[44:47]
	v_mfma_f32_16x16x32_bf16 v[36:39], v[84:87], v[188:191], v[36:39]
	v_mfma_f32_16x16x32_bf16 v[28:31], v[76:79], v[196:199], v[28:31]
	v_mfma_f32_16x16x32_bf16 v[20:23], v[84:87], v[196:199], v[20:23]
	v_mfma_f32_16x16x32_bf16 v[12:15], v[76:79], v[206:209], v[12:15]
	v_mfma_f32_16x16x32_bf16 v[4:7], v[84:87], v[206:209], v[4:7]
	v_mfma_f32_16x16x32_bf16 v[56:59], v[96:99], v[176:179], v[56:59]
	v_mfma_f32_16x16x32_bf16 v[48:51], v[104:107], v[176:179], v[48:51]
	v_mfma_f32_16x16x32_bf16 v[40:43], v[96:99], v[184:187], v[40:43]
	v_mfma_f32_16x16x32_bf16 v[32:35], v[104:107], v[184:187], v[32:35]
	v_mfma_f32_16x16x32_bf16 v[24:27], v[96:99], v[192:195], v[24:27]
	v_mfma_f32_16x16x32_bf16 v[16:19], v[104:107], v[192:195], v[16:19]
	v_mfma_f32_16x16x32_bf16 v[8:11], v[96:99], v[202:205], v[8:11]
	v_mfma_f32_16x16x32_bf16 v[0:3], v[104:107], v[202:205], v[0:3]
	v_mfma_f32_16x16x32_bf16 v[56:59], v[100:103], v[180:183], v[56:59]
	v_mfma_f32_16x16x32_bf16 v[48:51], v[108:111], v[180:183], v[48:51]
	v_mfma_f32_16x16x32_bf16 v[40:43], v[100:103], v[188:191], v[40:43]
	v_mfma_f32_16x16x32_bf16 v[32:35], v[108:111], v[188:191], v[32:35]
	v_mfma_f32_16x16x32_bf16 v[24:27], v[100:103], v[196:199], v[24:27]
	v_mfma_f32_16x16x32_bf16 v[16:19], v[108:111], v[196:199], v[16:19]
	v_mfma_f32_16x16x32_bf16 v[8:11], v[100:103], v[206:209], v[8:11]
	v_mfma_f32_16x16x32_bf16 v[0:3], v[108:111], v[206:209], v[0:3]
	s_wakeup
	s_setprio 0
	s_add_i32 s67, s67, 2
	s_add_u32 s4, s4, 0x100
	s_addc_u32 s5, s5, 0
	s_add_u32 s63, s63, 0x100
	s_addc_u32 s66, s66, 0
	s_cmp_gt_u32 s67, 29
	s_cbranch_scc0 .LBB0_1102
	s_branch .Lhd1102_X
.Lhd1102_B:
	s_add_u32 s34, s4, 0xfff80080
	s_addc_u32 s35, s5, -1
	s_add_i32 s68, 0, 0x10000
	s_cmp_eq_u32 s67, 28
	s_cselect_b32 s37, s25, s35
	s_cselect_b32 s36, s61, s34
	s_cselect_b32 s35, s23, s66
	s_cselect_b32 s34, s62, s63
	s_add_i32 s70, 0, 0x14000
	v_add_u32_e32 v84, s68, v173
	v_add_u32_e32 v108, s70, v173
	ds_read_b128 v[72:75], v84
	ds_read_b128 v[76:79], v84 offset:1024
	ds_read_b128 v[80:83], v84 offset:2048
	ds_read_b128 v[84:87], v84 offset:3072
	ds_read_b128 v[96:99], v108
	ds_read_b128 v[100:103], v108 offset:1024
	ds_read_b128 v[104:107], v108 offset:2048
	ds_read_b128 v[108:111], v108 offset:3072
	v_lshl_add_u64 v[170:171], s[4:5], 0, v[166:167]
	s_add_i32 m0, s31, 0xc000
	ds_read_b128 v[176:179], v174
	ds_read_b128 v[180:183], v174 offset:1024
	ds_read_b128 v[184:187], v174 offset:2048
	ds_read_b128 v[188:191], v174 offset:3072
	ds_read_b128 v[192:195], v174 offset:4096
	ds_read_b128 v[196:199], v174 offset:5120
	ds_read_b128 v[202:205], v174 offset:6144
	ds_read_b128 v[206:209], v174 offset:7168
	global_load_lds_dwordx4 v[170:171], off
	v_lshl_add_u64 v[170:171], s[4:5], 0, v[168:169]
	s_add_i32 m0, s31, 0xe000
	s_nop 0
	global_load_lds_dwordx4 v[170:171], off
	s_add_u32 vcc_lo, s4, 0xfff80000
	s_addc_u32 vcc_hi, s5, -1
	s_mov_b32 m0, s55
	s_nop 0
	global_load_lds_dwordx4 v164, vcc
	s_mov_b32 m0, s56
	s_nop 0
	global_load_lds_dwordx4 v162, vcc
	s_waitcnt vmcnt(4)
	s_waitcnt lgkmcnt(0)
	s_sleep 4
	s_setprio 1
	v_mfma_f32_16x16x32_bf16 v[156:159], v[72:75], v[176:179], v[156:159]
	v_mfma_f32_16x16x32_bf16 v[152:155], v[80:83], v[176:179], v[152:155]
	v_mfma_f32_16x16x32_bf16 v[140:143], v[72:75], v[184:187], v[140:143]
	v_mfma_f32_16x16x32_bf16 v[132:135], v[80:83], v[184:187], v[132:135]
	v_mfma_f32_16x16x32_bf16 v[124:127], v[72:75], v[192:195], v[124:127]
	v_mfma_f32_16x16x32_bf16 v[116:119], v[80:83], v[192:195], v[116:119]
	v_mfma_f32_16x16x32_bf16 v[92:95], v[72:75], v[202:205], v[92:95]
	v_mfma_f32_16x16x32_bf16 v[68:71], v[80:83], v[202:205], v[68:71]
	v_mfma_f32_16x16x32_bf16 v[156:159], v[76:79], v[180:183], v[156:159]
	v_mfma_f32_16x16x32_bf16 v[152:155], v[84:87], v[180:183], v[152:155]
	v_mfma_f32_16x16x32_bf16 v[140:143], v[76:79], v[188:191], v[140:143]
	v_mfma_f32_16x16x32_bf16 v[132:135], v[84:87], v[188:191], v[132:135]
	v_mfma_f32_16x16x32_bf16 v[124:127], v[76:79], v[196:199], v[124:127]
	v_mfma_f32_16x16x32_bf16 v[116:119], v[84:87], v[196:199], v[116:119]
	v_mfma_f32_16x16x32_bf16 v[92:95], v[76:79], v[206:209], v[92:95]
	v_mfma_f32_16x16x32_bf16 v[68:71], v[84:87], v[206:209], v[68:71]
	v_mfma_f32_16x16x32_bf16 v[148:151], v[96:99], v[176:179], v[148:151]
	v_mfma_f32_16x16x32_bf16 v[144:147], v[104:107], v[176:179], v[144:147]
	v_mfma_f32_16x16x32_bf16 v[136:139], v[96:99], v[184:187], v[136:139]
	v_mfma_f32_16x16x32_bf16 v[128:131], v[104:107], v[184:187], v[128:131]
	v_mfma_f32_16x16x32_bf16 v[120:123], v[96:99], v[192:195], v[120:123]
	v_mfma_f32_16x16x32_bf16 v[112:115], v[104:107], v[192:195], v[112:115]
	v_mfma_f32_16x16x32_bf16 v[88:91], v[96:99], v[202:205], v[88:91]
	v_mfma_f32_16x16x32_bf16 v[64:67], v[104:107], v[202:205], v[64:67]
	v_mfma_f32_16x16x32_bf16 v[148:151], v[100:103], v[180:183], v[148:151]
	v_mfma_f32_16x16x32_bf16 v[144:147], v[108:111], v[180:183], v[144:147]
	v_mfma_f32_16x16x32_bf16 v[136:139], v[100:103], v[188:191], v[136:139]
	v_mfma_f32_16x16x32_bf16 v[128:131], v[108:111], v[188:191], v[128:131]
	v_mfma_f32_16x16x32_bf16 v[120:123], v[100:103], v[196:199], v[120:123]
	v_mfma_f32_16x16x32_bf16 v[112:115], v[108:111], v[196:199], v[112:115]
	v_mfma_f32_16x16x32_bf16 v[88:91], v[100:103], v[206:209], v[88:91]
	v_mfma_f32_16x16x32_bf16 v[64:67], v[108:111], v[206:209], v[64:67]
	s_barrier
	s_setprio 0
	s_add_i32 s68, s68, s53
	v_lshl_add_u64 v[170:171], s[34:35], 0, v[200:201]
	s_mov_b32 m0, s68
	ds_read_b128 v[176:179], v174 offset:16384
	ds_read_b128 v[180:183], v174 offset:17408
	ds_read_b128 v[184:187], v174 offset:18432
	ds_read_b128 v[188:191], v174 offset:19456
	ds_read_b128 v[192:195], v174 offset:20480
	ds_read_b128 v[196:199], v174 offset:21504
	ds_read_b128 v[202:205], v174 offset:22528
	ds_read_b128 v[206:209], v174 offset:23552
	global_load_lds_dwordx4 v[170:171], off
	s_add_i32 m0, s68, 0x2000
	s_add_u32 s68, s34, 0x80000
	v_lshl_add_u64 v[212:213], s[34:35], 0, v[160:161]
	s_addc_u32 s69, s35, 0
	s_add_i32 s70, s70, s53
	global_load_lds_dwordx4 v[212:213], off
	v_lshl_add_u64 v[214:215], s[68:69], 0, v[200:201]
	s_mov_b32 m0, s70
	global_load_lds_dwordx4 v[214:215], off
	v_lshl_add_u64 v[214:215], s[68:69], 0, v[160:161]
	s_add_i32 m0, s70, 0x2000
	s_nop 0
	global_load_lds_dwordx4 v[214:215], off
	s_waitcnt vmcnt(4)
	s_waitcnt lgkmcnt(0)
	s_sleep 4
	s_setprio 1
	v_mfma_f32_16x16x32_bf16 v[60:63], v[72:75], v[176:179], v[60:63]
	v_mfma_f32_16x16x32_bf16 v[52:55], v[80:83], v[176:179], v[52:55]
	v_mfma_f32_16x16x32_bf16 v[44:47], v[72:75], v[184:187], v[44:47]
	v_mfma_f32_16x16x32_bf16 v[36:39], v[80:83], v[184:187], v[36:39]
	v_mfma_f32_16x16x32_bf16 v[28:31], v[72:75], v[192:195], v[28:31]
	v_mfma_f32_16x16x32_bf16 v[20:23], v[80:83], v[192:195], v[20:23]
	v_mfma_f32_16x16x32_bf16 v[12:15], v[72:75], v[202:205], v[12:15]
	v_mfma_f32_16x16x32_bf16 v[4:7], v[80:83], v[202:205], v[4:7]
	v_mfma_f32_16x16x32_bf16 v[60:63], v[76:79], v[180:183], v[60:63]
	v_mfma_f32_16x16x32_bf16 v[52:55], v[84:87], v[180:183], v[52:55]
	v_mfma_f32_16x16x32_bf16 v[44:47], v[76:79], v[188:191], v[44:47]
	v_mfma_f32_16x16x32_bf16 v[36:39], v[84:87], v[188:191], v[36:39]
	v_mfma_f32_16x16x32_bf16 v[28:31], v[76:79], v[196:199], v[28:31]
	v_mfma_f32_16x16x32_bf16 v[20:23], v[84:87], v[196:199], v[20:23]
	v_mfma_f32_16x16x32_bf16 v[12:15], v[76:79], v[206:209], v[12:15]
	v_mfma_f32_16x16x32_bf16 v[4:7], v[84:87], v[206:209], v[4:7]
	v_mfma_f32_16x16x32_bf16 v[56:59], v[96:99], v[176:179], v[56:59]
	v_mfma_f32_16x16x32_bf16 v[48:51], v[104:107], v[176:179], v[48:51]
	v_mfma_f32_16x16x32_bf16 v[40:43], v[96:99], v[184:187], v[40:43]
	v_mfma_f32_16x16x32_bf16 v[32:35], v[104:107], v[184:187], v[32:35]
	v_mfma_f32_16x16x32_bf16 v[24:27], v[96:99], v[192:195], v[24:27]
	v_mfma_f32_16x16x32_bf16 v[16:19], v[104:107], v[192:195], v[16:19]
	v_mfma_f32_16x16x32_bf16 v[8:11], v[96:99], v[202:205], v[8:11]
	v_mfma_f32_16x16x32_bf16 v[0:3], v[104:107], v[202:205], v[0:3]
	v_mfma_f32_16x16x32_bf16 v[56:59], v[100:103], v[180:183], v[56:59]
	v_mfma_f32_16x16x32_bf16 v[48:51], v[108:111], v[180:183], v[48:51]
	v_mfma_f32_16x16x32_bf16 v[40:43], v[100:103], v[188:191], v[40:43]
	v_mfma_f32_16x16x32_bf16 v[32:35], v[108:111], v[188:191], v[32:35]
	v_mfma_f32_16x16x32_bf16 v[24:27], v[100:103], v[196:199], v[24:27]
	v_mfma_f32_16x16x32_bf16 v[16:19], v[108:111], v[196:199], v[16:19]
	v_mfma_f32_16x16x32_bf16 v[8:11], v[100:103], v[206:209], v[8:11]
	v_mfma_f32_16x16x32_bf16 v[0:3], v[108:111], v[206:209], v[0:3]
	s_barrier
	s_setprio 0
	s_add_i32 s68, 0, 0x18000
	s_add_i32 s69, 0, 0x1c000
	v_add_u32_e32 v84, s68, v173
	v_add_u32_e32 v108, s69, v173
	ds_read_b128 v[72:75], v84
	ds_read_b128 v[76:79], v84 offset:1024
	ds_read_b128 v[80:83], v84 offset:2048
	ds_read_b128 v[84:87], v84 offset:3072
	ds_read_b128 v[96:99], v108
	ds_read_b128 v[100:103], v108 offset:1024
	ds_read_b128 v[104:107], v108 offset:2048
	ds_read_b128 v[108:111], v108 offset:3072
	s_mov_b32 m0, s31
	s_nop 0
	global_load_lds_dwordx4 v164, s[36:37]
	s_mov_b32 m0, s42
	s_nop 0
	global_load_lds_dwordx4 v162, s[36:37]
	s_add_u32 s36, s36, 0x80000
	s_addc_u32 s37, s37, 0
	s_mov_b32 m0, s43
	v_lshl_add_u64 v[218:219], s[36:37], 0, v[164:165]
	ds_read_b128 v[176:179], v174 offset:32768
	ds_read_b128 v[180:183], v174 offset:33792
	ds_read_b128 v[184:187], v174 offset:34816
	ds_read_b128 v[188:191], v174 offset:35840
	ds_read_b128 v[192:195], v174 offset:36864
	ds_read_b128 v[196:199], v174 offset:37888
	ds_read_b128 v[202:205], v174 offset:38912
	ds_read_b128 v[206:209], v174 offset:39936
	global_load_lds_dwordx4 v[218:219], off
	v_lshl_add_u64 v[218:219], s[36:37], 0, v[162:163]
	s_mov_b32 m0, s54
	s_nop 0
	global_load_lds_dwordx4 v[218:219], off
	s_waitcnt vmcnt(4)
	s_waitcnt lgkmcnt(0)
	s_sleep 4
	s_setprio 1
	v_mfma_f32_16x16x32_bf16 v[156:159], v[72:75], v[176:179], v[156:159]
	v_mfma_f32_16x16x32_bf16 v[152:155], v[80:83], v[176:179], v[152:155]
	v_mfma_f32_16x16x32_bf16 v[140:143], v[72:75], v[184:187], v[140:143]
	v_mfma_f32_16x16x32_bf16 v[132:135], v[80:83], v[184:187], v[132:135]
	v_mfma_f32_16x16x32_bf16 v[124:127], v[72:75], v[192:195], v[124:127]
	v_mfma_f32_16x16x32_bf16 v[116:119], v[80:83], v[192:195], v[116:119]
	v_mfma_f32_16x16x32_bf16 v[92:95], v[72:75], v[202:205], v[92:95]
	v_mfma_f32_16x16x32_bf16 v[68:71], v[80:83], v[202:205], v[68:71]
	v_mfma_f32_16x16x32_bf16 v[156:159], v[76:79], v[180:183], v[156:159]
	v_mfma_f32_16x16x32_bf16 v[152:155], v[84:87], v[180:183], v[152:155]
	v_mfma_f32_16x16x32_bf16 v[140:143], v[76:79], v[188:191], v[140:143]
	v_mfma_f32_16x16x32_bf16 v[132:135], v[84:87], v[188:191], v[132:135]
	v_mfma_f32_16x16x32_bf16 v[124:127], v[76:79], v[196:199], v[124:127]
	v_mfma_f32_16x16x32_bf16 v[116:119], v[84:87], v[196:199], v[116:119]
	v_mfma_f32_16x16x32_bf16 v[92:95], v[76:79], v[206:209], v[92:95]
	v_mfma_f32_16x16x32_bf16 v[68:71], v[84:87], v[206:209], v[68:71]
	v_mfma_f32_16x16x32_bf16 v[148:151], v[96:99], v[176:179], v[148:151]
	v_mfma_f32_16x16x32_bf16 v[144:147], v[104:107], v[176:179], v[144:147]
	v_mfma_f32_16x16x32_bf16 v[136:139], v[96:99], v[184:187], v[136:139]
	v_mfma_f32_16x16x32_bf16 v[128:131], v[104:107], v[184:187], v[128:131]
	v_mfma_f32_16x16x32_bf16 v[120:123], v[96:99], v[192:195], v[120:123]
	v_mfma_f32_16x16x32_bf16 v[112:115], v[104:107], v[192:195], v[112:115]
	v_mfma_f32_16x16x32_bf16 v[88:91], v[96:99], v[202:205], v[88:91]
	v_mfma_f32_16x16x32_bf16 v[64:67], v[104:107], v[202:205], v[64:67]
	v_mfma_f32_16x16x32_bf16 v[148:151], v[100:103], v[180:183], v[148:151]
	v_mfma_f32_16x16x32_bf16 v[144:147], v[108:111], v[180:183], v[144:147]
	v_mfma_f32_16x16x32_bf16 v[136:139], v[100:103], v[188:191], v[136:139]
	v_mfma_f32_16x16x32_bf16 v[128:131], v[108:111], v[188:191], v[128:131]
	v_mfma_f32_16x16x32_bf16 v[120:123], v[100:103], v[196:199], v[120:123]
	v_mfma_f32_16x16x32_bf16 v[112:115], v[108:111], v[196:199], v[112:115]
	v_mfma_f32_16x16x32_bf16 v[88:91], v[100:103], v[206:209], v[88:91]
	v_mfma_f32_16x16x32_bf16 v[64:67], v[108:111], v[206:209], v[64:67]
	s_barrier
	s_setprio 0
	s_add_i32 s36, s68, s53
	v_lshl_add_u64 v[170:171], v[170:171], 0, s[64:65]
	s_mov_b32 m0, s36
	ds_read_b128 v[176:179], v174 offset:49152
	ds_read_b128 v[180:183], v174 offset:50176
	ds_read_b128 v[184:187], v174 offset:51200
	ds_read_b128 v[188:191], v174 offset:52224
	ds_read_b128 v[192:195], v174 offset:53248
	ds_read_b128 v[196:199], v174 offset:54272
	ds_read_b128 v[202:205], v174 offset:55296
	ds_read_b128 v[206:209], v174 offset:56320
	global_load_lds_dwordx4 v[170:171], off
	s_add_i32 m0, s36, 0x2000
	s_add_u32 s34, s34, 0x80080
	v_lshl_add_u64 v[170:171], v[212:213], 0, s[64:65]
	s_addc_u32 s35, s35, 0
	s_add_i32 s36, s69, s53
	global_load_lds_dwordx4 v[170:171], off
	v_lshl_add_u64 v[170:171], s[34:35], 0, v[200:201]
	s_mov_b32 m0, s36
	s_nop 0
	global_load_lds_dwordx4 v[170:171], off
	v_lshl_add_u64 v[170:171], s[34:35], 0, v[160:161]
	s_add_i32 m0, s36, 0x2000
	s_nop 0
	global_load_lds_dwordx4 v[170:171], off
	s_waitcnt vmcnt(4)
	s_waitcnt lgkmcnt(0)
	s_sleep 4
	s_setprio 1
	v_mfma_f32_16x16x32_bf16 v[60:63], v[72:75], v[176:179], v[60:63]
	v_mfma_f32_16x16x32_bf16 v[52:55], v[80:83], v[176:179], v[52:55]
	v_mfma_f32_16x16x32_bf16 v[44:47], v[72:75], v[184:187], v[44:47]
	v_mfma_f32_16x16x32_bf16 v[36:39], v[80:83], v[184:187], v[36:39]
	v_mfma_f32_16x16x32_bf16 v[28:31], v[72:75], v[192:195], v[28:31]
	v_mfma_f32_16x16x32_bf16 v[20:23], v[80:83], v[192:195], v[20:23]
	v_mfma_f32_16x16x32_bf16 v[12:15], v[72:75], v[202:205], v[12:15]
	v_mfma_f32_16x16x32_bf16 v[4:7], v[80:83], v[202:205], v[4:7]
	v_mfma_f32_16x16x32_bf16 v[60:63], v[76:79], v[180:183], v[60:63]
	v_mfma_f32_16x16x32_bf16 v[52:55], v[84:87], v[180:183], v[52:55]
	v_mfma_f32_16x16x32_bf16 v[44:47], v[76:79], v[188:191], v[44:47]
	v_mfma_f32_16x16x32_bf16 v[36:39], v[84:87], v[188:191], v[36:39]
	v_mfma_f32_16x16x32_bf16 v[28:31], v[76:79], v[196:199], v[28:31]
	v_mfma_f32_16x16x32_bf16 v[20:23], v[84:87], v[196:199], v[20:23]
	v_mfma_f32_16x16x32_bf16 v[12:15], v[76:79], v[206:209], v[12:15]
	v_mfma_f32_16x16x32_bf16 v[4:7], v[84:87], v[206:209], v[4:7]
	v_mfma_f32_16x16x32_bf16 v[56:59], v[96:99], v[176:179], v[56:59]
	v_mfma_f32_16x16x32_bf16 v[48:51], v[104:107], v[176:179], v[48:51]
	v_mfma_f32_16x16x32_bf16 v[40:43], v[96:99], v[184:187], v[40:43]
	v_mfma_f32_16x16x32_bf16 v[32:35], v[104:107], v[184:187], v[32:35]
	v_mfma_f32_16x16x32_bf16 v[24:27], v[96:99], v[192:195], v[24:27]
	v_mfma_f32_16x16x32_bf16 v[16:19], v[104:107], v[192:195], v[16:19]
	v_mfma_f32_16x16x32_bf16 v[8:11], v[96:99], v[202:205], v[8:11]
	v_mfma_f32_16x16x32_bf16 v[0:3], v[104:107], v[202:205], v[0:3]
	v_mfma_f32_16x16x32_bf16 v[56:59], v[100:103], v[180:183], v[56:59]
	v_mfma_f32_16x16x32_bf16 v[48:51], v[108:111], v[180:183], v[48:51]
	v_mfma_f32_16x16x32_bf16 v[40:43], v[100:103], v[188:191], v[40:43]
	v_mfma_f32_16x16x32_bf16 v[32:35], v[108:111], v[188:191], v[32:35]
	v_mfma_f32_16x16x32_bf16 v[24:27], v[100:103], v[196:199], v[24:27]
	v_mfma_f32_16x16x32_bf16 v[16:19], v[108:111], v[196:199], v[16:19]
	v_mfma_f32_16x16x32_bf16 v[8:11], v[100:103], v[206:209], v[8:11]
	v_mfma_f32_16x16x32_bf16 v[0:3], v[108:111], v[206:209], v[0:3]
	s_barrier
	s_setprio 0
	s_add_i32 s67, s67, 2
	s_add_u32 s4, s4, 0x100
	s_addc_u32 s5, s5, 0
	s_add_u32 s63, s63, 0x100
	s_addc_u32 s66, s66, 0
	s_cmp_gt_u32 s67, 29
	s_cbranch_scc0 .Lhd1102_B
.Lhd1102_X:
	s_and_b64 vcc, exec, s[20:21]
	s_barrier

.LBB0_1109:
	v_and_b32_e32 v171, 15, v72
	s_lshl_b32 s5, s60, 8
	v_lshrrev_b32_e32 v72, 1, v72
	s_or_b32 s5, s5, s84
	v_and_b32_e32 v170, 24, v72
	v_or_b32_e32 v72, s5, v170
	v_ashrrev_i32_e32 v73, 31, v72
	v_lshlrev_b64 v[72:73], 2, v[72:73]
	v_lshl_add_u64 v[84:85], s[14:15], 0, v[72:73]
	v_lshl_add_u64 v[108:109], s[16:17], 0, v[72:73]
	global_load_dwordx4 v[72:75], v[84:85], off offset:16
	global_load_dwordx4 v[96:99], v[84:85], off
	global_load_dwordx4 v[76:79], v[108:109], off offset:16
	global_load_dwordx4 v[100:103], v[108:109], off
	global_load_dwordx4 v[80:83], v[84:85], off offset:528
	global_load_dwordx4 v[104:107], v[84:85], off offset:512
	s_nop 0
	global_load_dwordx4 v[84:87], v[108:109], off offset:528
	s_nop 0
	global_load_dwordx4 v[108:111], v[108:109], off offset:512
	s_lshl_b32 s4, s30, 8
	s_add_i32 s4, s4, s78
	v_or_b32_e32 v175, s4, v171
	v_readlane_b32 s4, v254, 7
	s_lshl_b32 s5, s60, 7
	s_or_b32 s5, s5, s84
	v_lshl_add_u32 v176, v171, 3, s4
	ds_read_b64 v[178:179], v176
	v_or_b32_e32 v170, s5, v170
	v_ashrrev_i32_e32 v171, 31, v170
	s_movk_i32 s23, 0x2c00
	s_andn2_b64 vcc, exec, s[2:3]
	s_waitcnt lgkmcnt(0)
	v_mul_f32_e64 v180, v179, -v178
	s_waitcnt vmcnt(0)
	v_pk_fma_f32 v[182:183], v[98:99], v[180:181], v[102:103] op_sel_hi:[1,0,1]
	v_pk_fma_f32 v[184:185], v[96:97], v[180:181], v[100:101] op_sel_hi:[1,0,1]
	v_pk_fma_f32 v[158:159], v[158:159], v[178:179], v[182:183] op_sel:[0,1,0]
	v_pk_fma_f32 v[156:157], v[156:157], v[178:179], v[184:185] op_sel:[0,1,0]
	v_pk_fma_f32 v[182:183], v[106:107], v[180:181], v[110:111] op_sel_hi:[1,0,1]
	v_pk_fma_f32 v[184:185], v[104:105], v[180:181], v[108:109] op_sel_hi:[1,0,1]
	v_pk_fma_f32 v[150:151], v[150:151], v[178:179], v[182:183] op_sel:[0,1,0]
	v_pk_fma_f32 v[148:149], v[148:149], v[178:179], v[184:185] op_sel:[0,1,0]
	v_pk_mul_f32 v[182:183], v[158:159], s[52:53] op_sel_hi:[1,0]
	v_pk_mul_f32 v[184:185], v[156:157], s[52:53] op_sel_hi:[1,0]
	v_exp_f32_e32 v182, v182
	v_exp_f32_e32 v184, v184
	v_exp_f32_e32 v185, v185
	v_exp_f32_e32 v183, v183
	v_pk_add_f32 v[184:185], v[184:185], 1.0 op_sel_hi:[1,0]
	v_pk_add_f32 v[182:183], v[182:183], 1.0 op_sel_hi:[1,0]
	v_rcp_f32_e32 v184, v184
	v_rcp_f32_e32 v185, v185
	v_rcp_f32_e32 v182, v182
	v_rcp_f32_e32 v183, v183
	v_pk_mul_f32 v[156:157], v[156:157], v[184:185]
	s_nop 0
	v_pk_mul_f32 v[148:149], v[148:149], v[156:157]
	v_pk_mul_f32 v[158:159], v[158:159], v[182:183]
	v_pk_fma_f32 v[156:157], v[74:75], v[180:181], v[78:79] op_sel_hi:[1,0,1]
	v_pk_mul_f32 v[150:151], v[150:151], v[158:159]
	v_pk_fma_f32 v[158:159], v[72:73], v[180:181], v[76:77] op_sel_hi:[1,0,1]
	v_pk_fma_f32 v[154:155], v[154:155], v[178:179], v[156:157] op_sel:[0,1,0]
	v_pk_fma_f32 v[152:153], v[152:153], v[178:179], v[158:159] op_sel:[0,1,0]
	v_pk_fma_f32 v[156:157], v[82:83], v[180:181], v[86:87] op_sel_hi:[1,0,1]
	v_pk_fma_f32 v[158:159], v[80:81], v[180:181], v[84:85] op_sel_hi:[1,0,1]
	v_pk_fma_f32 v[146:147], v[146:147], v[178:179], v[156:157] op_sel:[0,1,0]
	v_pk_fma_f32 v[144:145], v[144:145], v[178:179], v[158:159] op_sel:[0,1,0]
	v_pk_mul_f32 v[156:157], v[154:155], s[52:53] op_sel_hi:[1,0]
	v_pk_mul_f32 v[158:159], v[152:153], s[52:53] op_sel_hi:[1,0]
	v_exp_f32_e32 v156, v156
	v_exp_f32_e32 v158, v158
	v_exp_f32_e32 v159, v159
	v_exp_f32_e32 v157, v157
	v_pk_add_f32 v[158:159], v[158:159], 1.0 op_sel_hi:[1,0]
	v_pk_add_f32 v[156:157], v[156:157], 1.0 op_sel_hi:[1,0]
	v_rcp_f32_e32 v158, v158
	v_rcp_f32_e32 v159, v159
	v_rcp_f32_e32 v156, v156
	v_rcp_f32_e32 v157, v157
	v_pk_mul_f32 v[152:153], v[152:153], v[158:159]
	v_pk_mul_f32 v[154:155], v[154:155], v[156:157]
	s_nop 0
	v_pk_mul_f32 v[154:155], v[146:147], v[154:155]
	v_pk_mul_f32 v[146:147], v[144:145], v[152:153]
	v_cvt_pk_bf16_f32 v144, v148, v149
	v_mov_b64_e32 v[148:149], s[18:19]
	v_cvt_pk_bf16_f32 v145, v150, v151
	v_mad_i64_i32 v[152:153], s[4:5], v175, s23, v[148:149]
	v_lshlrev_b64 v[150:151], 1, v[170:171]
	v_lshl_add_u64 v[152:153], v[152:153], 0, v[150:151]
	v_cvt_pk_bf16_f32 v146, v146, v147
	v_cvt_pk_bf16_f32 v147, v154, v155
	global_store_dwordx4 v[152:153], v[144:147], off nt
	ds_read_b64 v[144:145], v176 offset:128
	s_waitcnt lgkmcnt(0)
	v_mul_f32_e64 v146, v145, -v144
	v_pk_fma_f32 v[152:153], v[98:99], v[146:147], v[102:103] op_sel_hi:[1,0,1]
	v_pk_fma_f32 v[154:155], v[96:97], v[146:147], v[100:101] op_sel_hi:[1,0,1]
	v_pk_fma_f32 v[142:143], v[142:143], v[144:145], v[152:153] op_sel:[0,1,0]
	v_pk_fma_f32 v[140:141], v[140:141], v[144:145], v[154:155] op_sel:[0,1,0]
	v_pk_fma_f32 v[152:153], v[106:107], v[146:147], v[110:111] op_sel_hi:[1,0,1]
	v_pk_fma_f32 v[154:155], v[104:105], v[146:147], v[108:109] op_sel_hi:[1,0,1]
	v_pk_fma_f32 v[138:139], v[138:139], v[144:145], v[152:153] op_sel:[0,1,0]
	v_pk_fma_f32 v[152:153], v[136:137], v[144:145], v[154:155] op_sel:[0,1,0]
	v_pk_mul_f32 v[136:137], v[142:143], s[52:53] op_sel_hi:[1,0]
	v_pk_mul_f32 v[154:155], v[140:141], s[52:53] op_sel_hi:[1,0]
	v_exp_f32_e32 v136, v136
	v_exp_f32_e32 v154, v154
	v_exp_f32_e32 v155, v155
	v_exp_f32_e32 v137, v137
	v_pk_add_f32 v[154:155], v[154:155], 1.0 op_sel_hi:[1,0]
	v_pk_add_f32 v[136:137], v[136:137], 1.0 op_sel_hi:[1,0]
	v_rcp_f32_e32 v154, v154
	v_rcp_f32_e32 v155, v155
	v_rcp_f32_e32 v136, v136
	v_rcp_f32_e32 v137, v137
	v_pk_mul_f32 v[140:141], v[140:141], v[154:155]
	v_pk_mul_f32 v[136:137], v[142:143], v[136:137]
	s_nop 0
	v_pk_mul_f32 v[136:137], v[138:139], v[136:137]
	v_pk_mul_f32 v[138:139], v[152:153], v[140:141]
	v_pk_fma_f32 v[140:141], v[74:75], v[146:147], v[78:79] op_sel_hi:[1,0,1]
	v_pk_fma_f32 v[142:143], v[72:73], v[146:147], v[76:77] op_sel_hi:[1,0,1]
	v_pk_fma_f32 v[134:135], v[134:135], v[144:145], v[140:141] op_sel:[0,1,0]
	v_pk_fma_f32 v[132:133], v[132:133], v[144:145], v[142:143] op_sel:[0,1,0]
	v_pk_fma_f32 v[140:141], v[82:83], v[146:147], v[86:87] op_sel_hi:[1,0,1]
	v_pk_fma_f32 v[142:143], v[80:81], v[146:147], v[84:85] op_sel_hi:[1,0,1]
	v_pk_fma_f32 v[130:131], v[130:131], v[144:145], v[140:141] op_sel:[0,1,0]
	v_pk_fma_f32 v[128:129], v[128:129], v[144:145], v[142:143] op_sel:[0,1,0]
	v_pk_mul_f32 v[140:141], v[134:135], s[52:53] op_sel_hi:[1,0]
	v_pk_mul_f32 v[142:143], v[132:133], s[52:53] op_sel_hi:[1,0]
	v_exp_f32_e32 v140, v140
	v_exp_f32_e32 v142, v142
	v_exp_f32_e32 v143, v143
	v_exp_f32_e32 v141, v141
	v_pk_add_f32 v[142:143], v[142:143], 1.0 op_sel_hi:[1,0]
	v_pk_add_f32 v[140:141], v[140:141], 1.0 op_sel_hi:[1,0]
	v_rcp_f32_e32 v142, v142
	v_rcp_f32_e32 v143, v143
	v_rcp_f32_e32 v140, v140
	v_rcp_f32_e32 v141, v141
	v_pk_mul_f32 v[132:133], v[132:133], v[142:143]
	v_pk_mul_f32 v[134:135], v[134:135], v[140:141]
	s_nop 0
	v_pk_mul_f32 v[134:135], v[130:131], v[134:135]
	v_pk_mul_f32 v[130:131], v[128:129], v[132:133]
	v_or_b32_e32 v132, 16, v175
	v_mad_i64_i32 v[132:133], s[4:5], v132, s23, v[148:149]
	v_cvt_pk_bf16_f32 v128, v138, v139
	v_cvt_pk_bf16_f32 v129, v136, v137
	v_lshl_add_u64 v[132:133], v[132:133], 0, v[150:151]
	v_cvt_pk_bf16_f32 v130, v130, v131
	v_cvt_pk_bf16_f32 v131, v134, v135
	global_store_dwordx4 v[132:133], v[128:131], off nt
	ds_read_b64 v[128:129], v176 offset:256
	s_waitcnt lgkmcnt(0)
	v_mul_f32_e64 v130, v129, -v128
	v_pk_fma_f32 v[132:133], v[98:99], v[130:131], v[102:103] op_sel_hi:[1,0,1]
	v_pk_fma_f32 v[134:135], v[96:97], v[130:131], v[100:101] op_sel_hi:[1,0,1]
	v_pk_fma_f32 v[126:127], v[126:127], v[128:129], v[132:133] op_sel:[0,1,0]
	v_pk_fma_f32 v[124:125], v[124:125], v[128:129], v[134:135] op_sel:[0,1,0]
	v_pk_fma_f32 v[132:133], v[106:107], v[130:131], v[110:111] op_sel_hi:[1,0,1]
	v_pk_fma_f32 v[134:135], v[104:105], v[130:131], v[108:109] op_sel_hi:[1,0,1]
	v_pk_fma_f32 v[122:123], v[122:123], v[128:129], v[132:133] op_sel:[0,1,0]
	v_pk_fma_f32 v[120:121], v[120:121], v[128:129], v[134:135] op_sel:[0,1,0]
	v_pk_mul_f32 v[132:133], v[126:127], s[52:53] op_sel_hi:[1,0]
	v_pk_mul_f32 v[134:135], v[124:125], s[52:53] op_sel_hi:[1,0]
	v_exp_f32_e32 v132, v132
	v_exp_f32_e32 v134, v134
	v_exp_f32_e32 v135, v135
	v_exp_f32_e32 v133, v133
	v_pk_add_f32 v[134:135], v[134:135], 1.0 op_sel_hi:[1,0]
	v_pk_add_f32 v[132:133], v[132:133], 1.0 op_sel_hi:[1,0]
	v_rcp_f32_e32 v134, v134
	v_rcp_f32_e32 v135, v135
	v_rcp_f32_e32 v132, v132
	v_rcp_f32_e32 v133, v133
	v_pk_mul_f32 v[124:125], v[124:125], v[134:135]
	s_nop 0
	v_pk_mul_f32 v[120:121], v[120:121], v[124:125]
	v_pk_mul_f32 v[126:127], v[126:127], v[132:133]
	v_pk_fma_f32 v[124:125], v[74:75], v[130:131], v[78:79] op_sel_hi:[1,0,1]
	v_pk_mul_f32 v[122:123], v[122:123], v[126:127]
	v_pk_fma_f32 v[126:127], v[72:73], v[130:131], v[76:77] op_sel_hi:[1,0,1]
	v_pk_fma_f32 v[118:119], v[118:119], v[128:129], v[124:125] op_sel:[0,1,0]
	v_pk_fma_f32 v[116:117], v[116:117], v[128:129], v[126:127] op_sel:[0,1,0]
	v_pk_fma_f32 v[124:125], v[82:83], v[130:131], v[86:87] op_sel_hi:[1,0,1]
	v_pk_fma_f32 v[126:127], v[80:81], v[130:131], v[84:85] op_sel_hi:[1,0,1]
	v_pk_fma_f32 v[114:115], v[114:115], v[128:129], v[124:125] op_sel:[0,1,0]
	v_pk_fma_f32 v[112:113], v[112:113], v[128:129], v[126:127] op_sel:[0,1,0]
	v_pk_mul_f32 v[124:125], v[118:119], s[52:53] op_sel_hi:[1,0]
	v_pk_mul_f32 v[126:127], v[116:117], s[52:53] op_sel_hi:[1,0]
	v_exp_f32_e32 v124, v124
	v_exp_f32_e32 v126, v126
	v_exp_f32_e32 v127, v127
	v_exp_f32_e32 v125, v125
	v_pk_add_f32 v[126:127], v[126:127], 1.0 op_sel_hi:[1,0]
	v_pk_add_f32 v[124:125], v[124:125], 1.0 op_sel_hi:[1,0]
	v_rcp_f32_e32 v126, v126
	v_rcp_f32_e32 v127, v127
	v_rcp_f32_e32 v124, v124
	v_rcp_f32_e32 v125, v125
	v_pk_mul_f32 v[116:117], v[116:117], v[126:127]
	v_pk_mul_f32 v[118:119], v[118:119], v[124:125]
	s_nop 0
	v_pk_mul_f32 v[118:119], v[114:115], v[118:119]
	v_pk_mul_f32 v[114:115], v[112:113], v[116:117]
	v_or_b32_e32 v116, 32, v175
	v_mad_i64_i32 v[116:117], s[4:5], v116, s23, v[148:149]
	v_cvt_pk_bf16_f32 v112, v120, v121
	v_cvt_pk_bf16_f32 v113, v122, v123
	v_lshl_add_u64 v[116:117], v[116:117], 0, v[150:151]
	v_cvt_pk_bf16_f32 v114, v114, v115
	v_cvt_pk_bf16_f32 v115, v118, v119
	global_store_dwordx4 v[116:117], v[112:115], off nt
	ds_read_b64 v[112:113], v176 offset:384
	s_waitcnt lgkmcnt(0)
	v_mul_f32_e64 v114, v113, -v112
	v_pk_fma_f32 v[116:117], v[98:99], v[114:115], v[102:103] op_sel_hi:[1,0,1]
	v_pk_fma_f32 v[118:119], v[96:97], v[114:115], v[100:101] op_sel_hi:[1,0,1]
	v_pk_fma_f32 v[94:95], v[94:95], v[112:113], v[116:117] op_sel:[0,1,0]
	v_pk_fma_f32 v[92:93], v[92:93], v[112:113], v[118:119] op_sel:[0,1,0]
	v_pk_fma_f32 v[116:117], v[106:107], v[114:115], v[110:111] op_sel_hi:[1,0,1]
	v_pk_fma_f32 v[118:119], v[104:105], v[114:115], v[108:109] op_sel_hi:[1,0,1]
	v_pk_fma_f32 v[90:91], v[90:91], v[112:113], v[116:117] op_sel:[0,1,0]
	v_pk_fma_f32 v[88:89], v[88:89], v[112:113], v[118:119] op_sel:[0,1,0]
	v_pk_mul_f32 v[116:117], v[94:95], s[52:53] op_sel_hi:[1,0]
	v_pk_mul_f32 v[118:119], v[92:93], s[52:53] op_sel_hi:[1,0]
	v_exp_f32_e32 v116, v116
	v_exp_f32_e32 v118, v118
	v_exp_f32_e32 v119, v119
	v_exp_f32_e32 v117, v117
	v_pk_add_f32 v[118:119], v[118:119], 1.0 op_sel_hi:[1,0]
	v_pk_add_f32 v[116:117], v[116:117], 1.0 op_sel_hi:[1,0]
	v_rcp_f32_e32 v118, v118
	v_rcp_f32_e32 v119, v119
	v_rcp_f32_e32 v116, v116
	v_rcp_f32_e32 v117, v117
	v_pk_mul_f32 v[92:93], v[92:93], v[118:119]
	s_nop 0
	v_pk_mul_f32 v[88:89], v[88:89], v[92:93]
	v_pk_mul_f32 v[94:95], v[94:95], v[116:117]
	v_pk_fma_f32 v[92:93], v[74:75], v[114:115], v[78:79] op_sel_hi:[1,0,1]
	v_pk_mul_f32 v[90:91], v[90:91], v[94:95]
	v_pk_fma_f32 v[94:95], v[72:73], v[114:115], v[76:77] op_sel_hi:[1,0,1]
	v_pk_fma_f32 v[70:71], v[70:71], v[112:113], v[92:93] op_sel:[0,1,0]
	v_pk_fma_f32 v[68:69], v[68:69], v[112:113], v[94:95] op_sel:[0,1,0]
	v_pk_fma_f32 v[92:93], v[82:83], v[114:115], v[86:87] op_sel_hi:[1,0,1]
	v_pk_fma_f32 v[94:95], v[80:81], v[114:115], v[84:85] op_sel_hi:[1,0,1]
	v_pk_fma_f32 v[66:67], v[66:67], v[112:113], v[92:93] op_sel:[0,1,0]
	v_pk_fma_f32 v[64:65], v[64:65], v[112:113], v[94:95] op_sel:[0,1,0]
	v_pk_mul_f32 v[92:93], v[70:71], s[52:53] op_sel_hi:[1,0]
	v_pk_mul_f32 v[94:95], v[68:69], s[52:53] op_sel_hi:[1,0]
	v_exp_f32_e32 v92, v92
	v_exp_f32_e32 v94, v94
	v_exp_f32_e32 v95, v95
	v_exp_f32_e32 v93, v93
	v_pk_add_f32 v[94:95], v[94:95], 1.0 op_sel_hi:[1,0]
	v_pk_add_f32 v[92:93], v[92:93], 1.0 op_sel_hi:[1,0]
	v_rcp_f32_e32 v94, v94
	v_rcp_f32_e32 v95, v95
	v_rcp_f32_e32 v92, v92
	v_rcp_f32_e32 v93, v93
	v_pk_mul_f32 v[68:69], v[68:69], v[94:95]
	v_pk_mul_f32 v[70:71], v[70:71], v[92:93]
	s_nop 0
	v_pk_mul_f32 v[70:71], v[66:67], v[70:71]
	v_pk_mul_f32 v[66:67], v[64:65], v[68:69]
	v_or_b32_e32 v68, 48, v175
	v_mad_i64_i32 v[68:69], s[4:5], v68, s23, v[148:149]
	v_cvt_pk_bf16_f32 v64, v88, v89
	v_cvt_pk_bf16_f32 v65, v90, v91
	v_lshl_add_u64 v[68:69], v[68:69], 0, v[150:151]
	v_cvt_pk_bf16_f32 v66, v66, v67
	v_cvt_pk_bf16_f32 v67, v70, v71
	global_store_dwordx4 v[68:69], v[64:67], off nt
	ds_read_b64 v[64:65], v176 offset:1024
	s_nop 0
	v_add_u32_e32 v67, 0x80, v175
	s_waitcnt lgkmcnt(0)
	v_mul_f32_e64 v66, v65, -v64
	v_pk_fma_f32 v[68:69], v[98:99], v[66:67], v[102:103] op_sel_hi:[1,0,1]
	v_pk_fma_f32 v[70:71], v[96:97], v[66:67], v[100:101] op_sel_hi:[1,0,1]
	v_pk_fma_f32 v[62:63], v[62:63], v[64:65], v[68:69] op_sel:[0,1,0]
	v_pk_fma_f32 v[60:61], v[60:61], v[64:65], v[70:71] op_sel:[0,1,0]
	v_pk_fma_f32 v[68:69], v[106:107], v[66:67], v[110:111] op_sel_hi:[1,0,1]
	v_pk_fma_f32 v[70:71], v[104:105], v[66:67], v[108:109] op_sel_hi:[1,0,1]
	v_pk_fma_f32 v[58:59], v[58:59], v[64:65], v[68:69] op_sel:[0,1,0]
	v_pk_fma_f32 v[56:57], v[56:57], v[64:65], v[70:71] op_sel:[0,1,0]
	v_pk_mul_f32 v[68:69], v[62:63], s[52:53] op_sel_hi:[1,0]
	v_pk_mul_f32 v[70:71], v[60:61], s[52:53] op_sel_hi:[1,0]
	v_exp_f32_e32 v68, v68
	v_exp_f32_e32 v70, v70
	v_exp_f32_e32 v71, v71
	v_exp_f32_e32 v69, v69
	v_pk_add_f32 v[70:71], v[70:71], 1.0 op_sel_hi:[1,0]
	v_pk_add_f32 v[68:69], v[68:69], 1.0 op_sel_hi:[1,0]
	v_rcp_f32_e32 v70, v70
	v_rcp_f32_e32 v71, v71
	v_rcp_f32_e32 v68, v68
	v_rcp_f32_e32 v69, v69
	v_pk_mul_f32 v[60:61], v[60:61], v[70:71]
	s_nop 0
	v_pk_mul_f32 v[56:57], v[56:57], v[60:61]
	v_pk_mul_f32 v[62:63], v[62:63], v[68:69]
	v_pk_fma_f32 v[60:61], v[74:75], v[66:67], v[78:79] op_sel_hi:[1,0,1]
	v_pk_mul_f32 v[58:59], v[58:59], v[62:63]
	v_pk_fma_f32 v[62:63], v[72:73], v[66:67], v[76:77] op_sel_hi:[1,0,1]
	v_pk_fma_f32 v[54:55], v[54:55], v[64:65], v[60:61] op_sel:[0,1,0]
	v_pk_fma_f32 v[52:53], v[52:53], v[64:65], v[62:63] op_sel:[0,1,0]
	v_pk_fma_f32 v[60:61], v[82:83], v[66:67], v[86:87] op_sel_hi:[1,0,1]
	v_pk_fma_f32 v[62:63], v[80:81], v[66:67], v[84:85] op_sel_hi:[1,0,1]
	v_pk_fma_f32 v[50:51], v[50:51], v[64:65], v[60:61] op_sel:[0,1,0]
	v_pk_fma_f32 v[48:49], v[48:49], v[64:65], v[62:63] op_sel:[0,1,0]
	v_pk_mul_f32 v[60:61], v[54:55], s[52:53] op_sel_hi:[1,0]
	v_pk_mul_f32 v[62:63], v[52:53], s[52:53] op_sel_hi:[1,0]
	v_exp_f32_e32 v60, v60
	v_exp_f32_e32 v62, v62
	v_exp_f32_e32 v63, v63
	v_exp_f32_e32 v61, v61
	v_pk_add_f32 v[62:63], v[62:63], 1.0 op_sel_hi:[1,0]
	v_pk_add_f32 v[60:61], v[60:61], 1.0 op_sel_hi:[1,0]
	v_rcp_f32_e32 v62, v62
	v_rcp_f32_e32 v63, v63
	v_rcp_f32_e32 v60, v60
	v_rcp_f32_e32 v61, v61
	v_pk_mul_f32 v[52:53], v[52:53], v[62:63]
	v_pk_mul_f32 v[54:55], v[54:55], v[60:61]
	s_nop 0
	v_pk_mul_f32 v[54:55], v[50:51], v[54:55]
	v_pk_mul_f32 v[50:51], v[48:49], v[52:53]
	v_mad_i64_i32 v[52:53], s[4:5], v67, s23, v[148:149]
	v_cvt_pk_bf16_f32 v48, v56, v57
	v_cvt_pk_bf16_f32 v49, v58, v59
	v_lshl_add_u64 v[52:53], v[52:53], 0, v[150:151]
	v_cvt_pk_bf16_f32 v50, v50, v51
	v_cvt_pk_bf16_f32 v51, v54, v55
	global_store_dwordx4 v[52:53], v[48:51], off nt
	ds_read_b64 v[48:49], v176 offset:1152
	s_waitcnt lgkmcnt(0)
	v_mul_f32_e64 v50, v49, -v48
	v_pk_fma_f32 v[52:53], v[98:99], v[50:51], v[102:103] op_sel_hi:[1,0,1]
	v_pk_fma_f32 v[54:55], v[96:97], v[50:51], v[100:101] op_sel_hi:[1,0,1]
	v_pk_fma_f32 v[46:47], v[46:47], v[48:49], v[52:53] op_sel:[0,1,0]
	v_pk_fma_f32 v[44:45], v[44:45], v[48:49], v[54:55] op_sel:[0,1,0]
	v_pk_fma_f32 v[52:53], v[106:107], v[50:51], v[110:111] op_sel_hi:[1,0,1]
	v_pk_fma_f32 v[54:55], v[104:105], v[50:51], v[108:109] op_sel_hi:[1,0,1]
	v_pk_fma_f32 v[42:43], v[42:43], v[48:49], v[52:53] op_sel:[0,1,0]
	v_pk_fma_f32 v[40:41], v[40:41], v[48:49], v[54:55] op_sel:[0,1,0]
	v_pk_mul_f32 v[52:53], v[46:47], s[52:53] op_sel_hi:[1,0]
	v_pk_mul_f32 v[54:55], v[44:45], s[52:53] op_sel_hi:[1,0]
	v_exp_f32_e32 v52, v52
	v_exp_f32_e32 v54, v54
	v_exp_f32_e32 v55, v55
	v_exp_f32_e32 v53, v53
	v_pk_add_f32 v[54:55], v[54:55], 1.0 op_sel_hi:[1,0]
	v_pk_add_f32 v[52:53], v[52:53], 1.0 op_sel_hi:[1,0]
	v_rcp_f32_e32 v54, v54
	v_rcp_f32_e32 v55, v55
	v_rcp_f32_e32 v52, v52
	v_rcp_f32_e32 v53, v53
	v_pk_mul_f32 v[44:45], v[44:45], v[54:55]
	s_nop 0
	v_pk_mul_f32 v[40:41], v[40:41], v[44:45]
	v_pk_mul_f32 v[46:47], v[46:47], v[52:53]
	v_pk_fma_f32 v[44:45], v[74:75], v[50:51], v[78:79] op_sel_hi:[1,0,1]
	v_pk_mul_f32 v[42:43], v[42:43], v[46:47]
	v_pk_fma_f32 v[46:47], v[72:73], v[50:51], v[76:77] op_sel_hi:[1,0,1]
	v_pk_fma_f32 v[38:39], v[38:39], v[48:49], v[44:45] op_sel:[0,1,0]
	v_pk_fma_f32 v[36:37], v[36:37], v[48:49], v[46:47] op_sel:[0,1,0]
	v_pk_fma_f32 v[44:45], v[82:83], v[50:51], v[86:87] op_sel_hi:[1,0,1]
	v_pk_fma_f32 v[46:47], v[80:81], v[50:51], v[84:85] op_sel_hi:[1,0,1]
	v_pk_fma_f32 v[34:35], v[34:35], v[48:49], v[44:45] op_sel:[0,1,0]
	v_pk_fma_f32 v[32:33], v[32:33], v[48:49], v[46:47] op_sel:[0,1,0]
	v_pk_mul_f32 v[44:45], v[38:39], s[52:53] op_sel_hi:[1,0]
	v_pk_mul_f32 v[46:47], v[36:37], s[52:53] op_sel_hi:[1,0]
	v_exp_f32_e32 v44, v44
	v_exp_f32_e32 v46, v46
	v_exp_f32_e32 v47, v47
	v_exp_f32_e32 v45, v45
	v_pk_add_f32 v[46:47], v[46:47], 1.0 op_sel_hi:[1,0]
	v_pk_add_f32 v[44:45], v[44:45], 1.0 op_sel_hi:[1,0]
	v_rcp_f32_e32 v46, v46
	v_rcp_f32_e32 v47, v47
	v_rcp_f32_e32 v44, v44
	v_rcp_f32_e32 v45, v45
	v_pk_mul_f32 v[36:37], v[36:37], v[46:47]
	v_pk_mul_f32 v[38:39], v[38:39], v[44:45]
	s_nop 0
	v_pk_mul_f32 v[38:39], v[34:35], v[38:39]
	v_pk_mul_f32 v[34:35], v[32:33], v[36:37]
	v_add_u32_e32 v36, 0x90, v175
	v_mad_i64_i32 v[36:37], s[4:5], v36, s23, v[148:149]
	v_cvt_pk_bf16_f32 v32, v40, v41
	v_cvt_pk_bf16_f32 v33, v42, v43
	v_lshl_add_u64 v[36:37], v[36:37], 0, v[150:151]
	v_cvt_pk_bf16_f32 v34, v34, v35
	v_cvt_pk_bf16_f32 v35, v38, v39
	global_store_dwordx4 v[36:37], v[32:35], off nt
	ds_read_b64 v[32:33], v176 offset:1280
	s_waitcnt lgkmcnt(0)
	v_mul_f32_e64 v34, v33, -v32
	v_pk_fma_f32 v[36:37], v[98:99], v[34:35], v[102:103] op_sel_hi:[1,0,1]
	v_pk_fma_f32 v[38:39], v[96:97], v[34:35], v[100:101] op_sel_hi:[1,0,1]
	v_pk_fma_f32 v[30:31], v[30:31], v[32:33], v[36:37] op_sel:[0,1,0]
	v_pk_fma_f32 v[28:29], v[28:29], v[32:33], v[38:39] op_sel:[0,1,0]
	v_pk_fma_f32 v[36:37], v[106:107], v[34:35], v[110:111] op_sel_hi:[1,0,1]
	v_pk_fma_f32 v[38:39], v[104:105], v[34:35], v[108:109] op_sel_hi:[1,0,1]
	v_pk_fma_f32 v[26:27], v[26:27], v[32:33], v[36:37] op_sel:[0,1,0]
	v_pk_fma_f32 v[24:25], v[24:25], v[32:33], v[38:39] op_sel:[0,1,0]
	v_pk_mul_f32 v[36:37], v[30:31], s[52:53] op_sel_hi:[1,0]
	v_pk_mul_f32 v[38:39], v[28:29], s[52:53] op_sel_hi:[1,0]
	v_exp_f32_e32 v36, v36
	v_exp_f32_e32 v38, v38
	v_exp_f32_e32 v39, v39
	v_exp_f32_e32 v37, v37
	v_pk_add_f32 v[38:39], v[38:39], 1.0 op_sel_hi:[1,0]
	v_pk_add_f32 v[36:37], v[36:37], 1.0 op_sel_hi:[1,0]
	v_rcp_f32_e32 v38, v38
	v_rcp_f32_e32 v39, v39
	v_rcp_f32_e32 v36, v36
	v_rcp_f32_e32 v37, v37
	v_pk_mul_f32 v[28:29], v[28:29], v[38:39]
	s_nop 0
	v_pk_mul_f32 v[24:25], v[24:25], v[28:29]
	v_pk_mul_f32 v[30:31], v[30:31], v[36:37]
	v_pk_fma_f32 v[28:29], v[74:75], v[34:35], v[78:79] op_sel_hi:[1,0,1]
	v_pk_mul_f32 v[26:27], v[26:27], v[30:31]
	v_pk_fma_f32 v[30:31], v[72:73], v[34:35], v[76:77] op_sel_hi:[1,0,1]
	v_pk_fma_f32 v[22:23], v[22:23], v[32:33], v[28:29] op_sel:[0,1,0]
	v_pk_fma_f32 v[20:21], v[20:21], v[32:33], v[30:31] op_sel:[0,1,0]
	v_pk_fma_f32 v[28:29], v[82:83], v[34:35], v[86:87] op_sel_hi:[1,0,1]
	v_pk_fma_f32 v[30:31], v[80:81], v[34:35], v[84:85] op_sel_hi:[1,0,1]
	v_pk_fma_f32 v[18:19], v[18:19], v[32:33], v[28:29] op_sel:[0,1,0]
	v_pk_fma_f32 v[16:17], v[16:17], v[32:33], v[30:31] op_sel:[0,1,0]
	v_pk_mul_f32 v[28:29], v[22:23], s[52:53] op_sel_hi:[1,0]
	v_pk_mul_f32 v[30:31], v[20:21], s[52:53] op_sel_hi:[1,0]
	v_exp_f32_e32 v28, v28
	v_exp_f32_e32 v30, v30
	v_exp_f32_e32 v31, v31
	v_exp_f32_e32 v29, v29
	v_pk_add_f32 v[30:31], v[30:31], 1.0 op_sel_hi:[1,0]
	v_pk_add_f32 v[28:29], v[28:29], 1.0 op_sel_hi:[1,0]
	v_rcp_f32_e32 v30, v30
	v_rcp_f32_e32 v31, v31
	v_rcp_f32_e32 v28, v28
	v_rcp_f32_e32 v29, v29
	v_pk_mul_f32 v[20:21], v[20:21], v[30:31]
	v_pk_mul_f32 v[22:23], v[22:23], v[28:29]
	s_nop 0
	v_pk_mul_f32 v[22:23], v[18:19], v[22:23]
	v_pk_mul_f32 v[18:19], v[16:17], v[20:21]
	v_add_u32_e32 v20, 0xa0, v175
	v_mad_i64_i32 v[20:21], s[4:5], v20, s23, v[148:149]
	v_cvt_pk_bf16_f32 v16, v24, v25
	v_cvt_pk_bf16_f32 v17, v26, v27
	v_lshl_add_u64 v[20:21], v[20:21], 0, v[150:151]
	v_cvt_pk_bf16_f32 v18, v18, v19
	v_cvt_pk_bf16_f32 v19, v22, v23
	global_store_dwordx4 v[20:21], v[16:19], off nt
	ds_read_b64 v[16:17], v176 offset:1408
	s_waitcnt lgkmcnt(0)
	v_mul_f32_e64 v18, v17, -v16
	v_pk_fma_f32 v[20:21], v[98:99], v[18:19], v[102:103] op_sel_hi:[1,0,1]
	v_pk_fma_f32 v[22:23], v[96:97], v[18:19], v[100:101] op_sel_hi:[1,0,1]
	v_pk_fma_f32 v[14:15], v[14:15], v[16:17], v[20:21] op_sel:[0,1,0]
	v_pk_fma_f32 v[12:13], v[12:13], v[16:17], v[22:23] op_sel:[0,1,0]
	v_pk_fma_f32 v[20:21], v[106:107], v[18:19], v[110:111] op_sel_hi:[1,0,1]
	v_pk_fma_f32 v[22:23], v[104:105], v[18:19], v[108:109] op_sel_hi:[1,0,1]
	v_pk_fma_f32 v[10:11], v[10:11], v[16:17], v[20:21] op_sel:[0,1,0]
	v_pk_fma_f32 v[8:9], v[8:9], v[16:17], v[22:23] op_sel:[0,1,0]
	v_pk_mul_f32 v[20:21], v[14:15], s[52:53] op_sel_hi:[1,0]
	v_pk_mul_f32 v[22:23], v[12:13], s[52:53] op_sel_hi:[1,0]
	v_exp_f32_e32 v20, v20
	v_exp_f32_e32 v22, v22
	v_exp_f32_e32 v23, v23
	v_exp_f32_e32 v21, v21
	v_pk_add_f32 v[22:23], v[22:23], 1.0 op_sel_hi:[1,0]
	v_pk_add_f32 v[20:21], v[20:21], 1.0 op_sel_hi:[1,0]
	v_rcp_f32_e32 v22, v22
	v_rcp_f32_e32 v23, v23
	v_rcp_f32_e32 v20, v20
	v_rcp_f32_e32 v21, v21
	v_pk_mul_f32 v[12:13], v[12:13], v[22:23]
	s_nop 0
	v_pk_mul_f32 v[8:9], v[8:9], v[12:13]
	v_pk_mul_f32 v[14:15], v[14:15], v[20:21]
	v_pk_fma_f32 v[12:13], v[74:75], v[18:19], v[78:79] op_sel_hi:[1,0,1]
	v_pk_mul_f32 v[10:11], v[10:11], v[14:15]
	v_pk_fma_f32 v[14:15], v[72:73], v[18:19], v[76:77] op_sel_hi:[1,0,1]
	v_pk_fma_f32 v[6:7], v[6:7], v[16:17], v[12:13] op_sel:[0,1,0]
	v_pk_fma_f32 v[4:5], v[4:5], v[16:17], v[14:15] op_sel:[0,1,0]
	v_pk_fma_f32 v[12:13], v[82:83], v[18:19], v[86:87] op_sel_hi:[1,0,1]
	v_pk_fma_f32 v[14:15], v[80:81], v[18:19], v[84:85] op_sel_hi:[1,0,1]
	v_pk_fma_f32 v[2:3], v[2:3], v[16:17], v[12:13] op_sel:[0,1,0]
	v_pk_fma_f32 v[0:1], v[0:1], v[16:17], v[14:15] op_sel:[0,1,0]
	v_pk_mul_f32 v[12:13], v[6:7], s[52:53] op_sel_hi:[1,0]
	v_pk_mul_f32 v[14:15], v[4:5], s[52:53] op_sel_hi:[1,0]
	v_exp_f32_e32 v12, v12
	v_exp_f32_e32 v14, v14
	v_exp_f32_e32 v15, v15
	v_exp_f32_e32 v13, v13
	v_pk_add_f32 v[14:15], v[14:15], 1.0 op_sel_hi:[1,0]
	v_pk_add_f32 v[12:13], v[12:13], 1.0 op_sel_hi:[1,0]
	v_rcp_f32_e32 v14, v14
	v_rcp_f32_e32 v15, v15
	v_rcp_f32_e32 v12, v12
	v_rcp_f32_e32 v13, v13
	v_pk_mul_f32 v[4:5], v[4:5], v[14:15]
	v_pk_mul_f32 v[6:7], v[6:7], v[12:13]
	s_nop 0
	v_pk_mul_f32 v[6:7], v[2:3], v[6:7]
	v_pk_mul_f32 v[2:3], v[0:1], v[4:5]
	v_add_u32_e32 v4, 0xb0, v175
	v_mad_i64_i32 v[4:5], s[4:5], v4, s23, v[148:149]
	v_lshl_add_u64 v[4:5], v[4:5], 0, v[150:151]
	s_mov_b64 s[4:5], -1
	v_cvt_pk_bf16_f32 v0, v8, v9
	v_cvt_pk_bf16_f32 v1, v10, v11
	v_cvt_pk_bf16_f32 v2, v2, v3
	v_cvt_pk_bf16_f32 v3, v6, v7
	global_store_dwordx4 v[4:5], v[0:3], off nt
	s_cbranch_vccnz .LBB0_1098
	s_andn2_b64 vcc, exec, s[10:11]
	s_cbranch_vccnz .LBB0_1097
	s_branch .LBB0_1097
